# removed the redundant back-to-back s_setprio 0/1 pairs in the middle of each 32-MFMA block of the six GEMM K-loops
# baseline (speedup 1.0000x reference)
; #define PG8_STAGE(bufoff, gbase, voff) do { _Pragma("unroll") for (int _i = 0; _i < 2; ++_i) \
;         __builtin_amdgcn_global_load_lds((const unsigned*)((const char*)(gbase) + (voff)[_i]), (LAS unsigned*)(lds + (bufoff) + ldsw + _i * 8192), 16, 0, 0); } while (0)
; #define PG8_LDA(dst, b, h) do { _Pragma("unroll") for (int m = 0; m < 4; ++m) _Pragma("unroll") for (int k = 0; k < 2; ++k) dst[m][k] = *(const LAS bf16x8*)(lds + PG8_SA(b, h) + aoff + m * 2048 + k * 1024); } while (0)
; #define PG8_LDB(dst, b, h) do { _Pragma("unroll") for (int n = 0; n < 2; ++n) _Pragma("unroll") for (int k = 0; k < 2; ++k) dst[n][k] = *(const LAS bf16x8*)(lds + PG8_SB(b, h) + boff + n * 2048 + k * 1024); } while (0)
; #define PG8_MMA(ai, bj, At, Bt) do { __builtin_amdgcn_s_setprio(1); _Pragma("unroll") for (int k = 0; k < 2; ++k) _Pragma("unroll") for (int m = 0; m < 4; ++m) _Pragma("unroll") for (int n = 0; n < 2; ++n) \
;         acc[ai][bj][m][n] = __builtin_amdgcn_mfma_f32_16x16x32_bf16(Bt[n][k], At[m][k], acc[ai][bj][m][n], 0, 0, 0); __builtin_amdgcn_s_setprio(0); } while (0)
; #define PG8_WAIT_V(n) asm volatile("s_waitcnt vmcnt(" #n ")" ::: "memory")
; #define PG8_WAIT_L(n) asm volatile("s_waitcnt lgkmcnt(" #n ")" ::: "memory")
; #define PG8_BAR __builtin_amdgcn_s_barrier()
; #define PG8_SCHED __builtin_amdgcn_sched_barrier(0)
; template <class Epi, bool ALIGN_EPI>
; __device__ __forceinline__ void gemm_phase(LAS unsigned char* lds, const Gemm g, const StaticOrder& S, const Epi& E, const int tid) {
;     ...
;             const bool last = (t == nt - 2);
;             const char* a1 = cA + (size_t)(t + 1) * kstep;
;             const char* a2 = last ? nA : cA + (size_t)(t + 2) * kstep; const char* b2 = last ? nB : cB + (size_t)(t + 2) * kstep;
;             const char* a3 = a2 + kstep; const char* b3 = b2 + kstep;
;             PG8_LDB(B0, 0, 0); PG8_LDB(B1, 0, 1); PG8_SCHED; PG8_LDA(At, 0, 0); PG8_STAGE(PG8_SA(1, 1), a1 + hA, voffA);
;             PG8_WAIT_V(8); PG8_WAIT_L(0); PG8_BAR; PG8_MMA(0, 0, At, B0); PG8_MMA(0, 1, At, B1); PG8_BAR; PG8_SCHED;
;             PG8_LDA(At, 0, 1); PG8_STAGE(PG8_SB(0, 0), b2, voffB); PG8_STAGE(PG8_SB(0, 1), b2 + hB, voffB); PG8_STAGE(PG8_SA(0, 0), a2, voffA);
;             PG8_WAIT_V(8); PG8_WAIT_L(0); PG8_BAR; PG8_MMA(1, 0, At, B0); PG8_MMA(1, 1, At, B1); PG8_BAR; PG8_SCHED;
.LBB0_236:
	s_add_i32 s47, s46, 2
	s_cmp_eq_u32 s60, s46
	s_cselect_b64 vcc, -1, 0
	s_cselect_b32 s71, s15, s13
	s_cselect_b32 s70, s14, s12
	s_add_i32 s46, 0, 0x14000
	v_lshl_add_u64 v[130:131], v[128:129], 0, s[92:93]
	v_add_u32_e32 v142, s33, v218
	v_add_u32_e32 v166, s46, v218
	v_cndmask_b32_e32 v159, v131, v165, vcc
	v_cndmask_b32_e32 v158, v130, v164, vcc
	ds_read_b128 v[130:133], v142
	ds_read_b128 v[134:137], v142 offset:1024
	ds_read_b128 v[138:141], v142 offset:2048
	ds_read_b128 v[142:145], v142 offset:3072
	ds_read_b128 v[146:149], v166
	ds_read_b128 v[150:153], v166 offset:1024
	ds_read_b128 v[154:157], v166 offset:2048
	ds_read_b128 v[186:189], v166 offset:3072
	v_lshl_add_u64 v[166:167], v[128:129], 0, v[160:161]
	s_add_i32 m0, s53, 0xc000
	ds_read_b128 v[190:193], v219
	ds_read_b128 v[194:197], v219 offset:1024
	ds_read_b128 v[198:201], v219 offset:2048
	ds_read_b128 v[202:205], v219 offset:3072
	ds_read_b128 v[206:209], v219 offset:4096
	ds_read_b128 v[210:213], v219 offset:5120
	ds_read_b128 v[240:243], v219 offset:6144
	ds_read_b128 v[244:247], v219 offset:7168
	global_load_lds_dwordx4 v[166:167], off
	v_lshl_add_u64 v[166:167], v[128:129], 0, v[162:163]
	s_add_i32 m0, s53, 0xe000
	s_nop 0
	global_load_lds_dwordx4 v[166:167], off
	s_waitcnt vmcnt(8)
	s_waitcnt lgkmcnt(0)
	s_barrier
	s_setprio 1
	s_waitcnt lgkmcnt(0)
	v_mfma_f32_16x16x32_bf16 v[120:123], v[130:133], v[190:193], v[120:123]
	v_mfma_f32_16x16x32_bf16 v[124:127], v[138:141], v[190:193], v[124:127]
	v_mfma_f32_16x16x32_bf16 v[108:111], v[130:133], v[198:201], v[108:111]
	v_mfma_f32_16x16x32_bf16 v[104:107], v[138:141], v[198:201], v[104:107]
	v_mfma_f32_16x16x32_bf16 v[92:95], v[130:133], v[206:209], v[92:95]
	v_mfma_f32_16x16x32_bf16 v[88:91], v[138:141], v[206:209], v[88:91]
	v_mfma_f32_16x16x32_bf16 v[76:79], v[130:133], v[240:243], v[76:79]
	v_mfma_f32_16x16x32_bf16 v[72:75], v[138:141], v[240:243], v[72:75]
	v_mfma_f32_16x16x32_bf16 v[120:123], v[134:137], v[194:197], v[120:123]
	v_mfma_f32_16x16x32_bf16 v[124:127], v[142:145], v[194:197], v[124:127]
	v_mfma_f32_16x16x32_bf16 v[108:111], v[134:137], v[202:205], v[108:111]
	v_mfma_f32_16x16x32_bf16 v[104:107], v[142:145], v[202:205], v[104:107]
	v_mfma_f32_16x16x32_bf16 v[92:95], v[134:137], v[210:213], v[92:95]
	v_mfma_f32_16x16x32_bf16 v[88:91], v[142:145], v[210:213], v[88:91]
	v_mfma_f32_16x16x32_bf16 v[76:79], v[134:137], v[244:247], v[76:79]
	v_mfma_f32_16x16x32_bf16 v[72:75], v[142:145], v[244:247], v[72:75]
	v_mfma_f32_16x16x32_bf16 v[116:119], v[146:149], v[190:193], v[116:119]
	v_mfma_f32_16x16x32_bf16 v[112:115], v[154:157], v[190:193], v[112:115]
	v_mfma_f32_16x16x32_bf16 v[100:103], v[146:149], v[198:201], v[100:103]
	v_mfma_f32_16x16x32_bf16 v[96:99], v[154:157], v[198:201], v[96:99]
	v_mfma_f32_16x16x32_bf16 v[84:87], v[146:149], v[206:209], v[84:87]
	v_mfma_f32_16x16x32_bf16 v[80:83], v[154:157], v[206:209], v[80:83]
	v_mfma_f32_16x16x32_bf16 v[68:71], v[146:149], v[240:243], v[68:71]
	v_mfma_f32_16x16x32_bf16 v[64:67], v[154:157], v[240:243], v[64:67]
	v_mfma_f32_16x16x32_bf16 v[116:119], v[150:153], v[194:197], v[116:119]
	v_mfma_f32_16x16x32_bf16 v[112:115], v[186:189], v[194:197], v[112:115]
	v_mfma_f32_16x16x32_bf16 v[100:103], v[150:153], v[202:205], v[100:103]
	v_mfma_f32_16x16x32_bf16 v[96:99], v[186:189], v[202:205], v[96:99]
	v_mfma_f32_16x16x32_bf16 v[84:87], v[150:153], v[210:213], v[84:87]
	v_mfma_f32_16x16x32_bf16 v[80:83], v[186:189], v[210:213], v[80:83]
	v_mfma_f32_16x16x32_bf16 v[68:71], v[150:153], v[244:247], v[68:71]
	v_mfma_f32_16x16x32_bf16 v[64:67], v[186:189], v[244:247], v[64:67]
	s_setprio 0
	s_barrier
	s_add_i32 s72, s33, s52
	v_lshl_add_u64 v[166:167], s[70:71], 0, v[180:181]
	s_mov_b32 m0, s72
	ds_read_b128 v[190:193], v219 offset:16384
	ds_read_b128 v[194:197], v219 offset:17408
	ds_read_b128 v[198:201], v219 offset:18432
	ds_read_b128 v[202:205], v219 offset:19456
	ds_read_b128 v[206:209], v219 offset:20480
	ds_read_b128 v[210:213], v219 offset:21504
	ds_read_b128 v[240:243], v219 offset:22528
	ds_read_b128 v[244:247], v219 offset:23552
	global_load_lds_dwordx4 v[166:167], off
	s_add_i32 m0, s72, 0x2000
	v_lshl_add_u64 v[214:215], s[70:71], 0, v[184:185]
	s_add_u32 s70, s70, s49
	s_addc_u32 s71, s71, 0
	s_add_i32 s46, s46, s52
	global_load_lds_dwordx4 v[214:215], off
	v_lshl_add_u64 v[220:221], s[70:71], 0, v[180:181]
	s_mov_b32 m0, s46
	v_lshl_add_u64 v[226:227], s[70:71], 0, v[184:185]
	global_load_lds_dwordx4 v[220:221], off
	s_add_i32 m0, s46, 0x2000
	v_lshl_add_u64 v[248:249], v[158:159], 0, v[178:179]
	global_load_lds_dwordx4 v[226:227], off
	s_mov_b32 m0, s53
	v_lshl_add_u64 v[250:251], v[158:159], 0, v[182:183]
	global_load_lds_dwordx4 v[248:249], off
	s_mov_b32 m0, s54
	s_nop 0
	global_load_lds_dwordx4 v[250:251], off
	s_waitcnt vmcnt(8)
	s_waitcnt lgkmcnt(0)
	s_barrier
; #define PG8_STAGE(bufoff, gbase, voff) do { _Pragma("unroll") for (int _i = 0; _i < 2; ++_i) \
;         __builtin_amdgcn_global_load_lds((const unsigned*)((const char*)(gbase) + (voff)[_i]), (LAS unsigned*)(lds + (bufoff) + ldsw + _i * 8192), 16, 0, 0); } while (0)
; #define PG8_LDA(dst, b, h) do { _Pragma("unroll") for (int m = 0; m < 4; ++m) _Pragma("unroll") for (int k = 0; k < 2; ++k) dst[m][k] = *(const LAS bf16x8*)(lds + PG8_SA(b, h) + aoff + m * 2048 + k * 1024); } while (0)
; #define PG8_LDB(dst, b, h) do { _Pragma("unroll") for (int n = 0; n < 2; ++n) _Pragma("unroll") for (int k = 0; k < 2; ++k) dst[n][k] = *(const LAS bf16x8*)(lds + PG8_SB(b, h) + boff + n * 2048 + k * 1024); } while (0)
; #define PG8_MMA(ai, bj, At, Bt) do { __builtin_amdgcn_s_setprio(1); _Pragma("unroll") for (int k = 0; k < 2; ++k) _Pragma("unroll") for (int m = 0; m < 4; ++m) _Pragma("unroll") for (int n = 0; n < 2; ++n) \
;         acc[ai][bj][m][n] = __builtin_amdgcn_mfma_f32_16x16x32_bf16(Bt[n][k], At[m][k], acc[ai][bj][m][n], 0, 0, 0); __builtin_amdgcn_s_setprio(0); } while (0)
; #define PG8_WAIT_V(n) asm volatile("s_waitcnt vmcnt(" #n ")" ::: "memory")
; #define PG8_WAIT_L(n) asm volatile("s_waitcnt lgkmcnt(" #n ")" ::: "memory")
; #define PG8_BAR __builtin_amdgcn_s_barrier()
; #define PG8_SCHED __builtin_amdgcn_sched_barrier(0)
; template <class Epi, bool ALIGN_EPI>
; __device__ __forceinline__ void gemm_phase(LAS unsigned char* lds, const Gemm g, const StaticOrder& S, const Epi& E, const int tid) {
;     ...
;             PG8_WAIT_V(8); PG8_WAIT_L(0); PG8_BAR; PG8_MMA(1, 0, At, B0); PG8_MMA(1, 1, At, B1); PG8_BAR; PG8_SCHED;
;             PG8_LDB(B0, 1, 0); PG8_LDB(B1, 1, 1); PG8_SCHED; PG8_LDA(At, 1, 0); PG8_STAGE(PG8_SA(0, 1), a2 + hA, voffA);
;             PG8_WAIT_V(8); PG8_WAIT_L(0); PG8_BAR; PG8_MMA(0, 0, At, B0); PG8_MMA(0, 1, At, B1); PG8_BAR; PG8_SCHED;
	s_setprio 1
	s_waitcnt lgkmcnt(0)
	v_mfma_f32_16x16x32_bf16 v[60:63], v[130:133], v[190:193], v[60:63]
	v_mfma_f32_16x16x32_bf16 v[56:59], v[138:141], v[190:193], v[56:59]
	v_mfma_f32_16x16x32_bf16 v[44:47], v[130:133], v[198:201], v[44:47]
	v_mfma_f32_16x16x32_bf16 v[40:43], v[138:141], v[198:201], v[40:43]
	v_mfma_f32_16x16x32_bf16 v[28:31], v[130:133], v[206:209], v[28:31]
	v_mfma_f32_16x16x32_bf16 v[24:27], v[138:141], v[206:209], v[24:27]
	v_mfma_f32_16x16x32_bf16 v[12:15], v[130:133], v[240:243], v[12:15]
	v_mfma_f32_16x16x32_bf16 v[8:11], v[138:141], v[240:243], v[8:11]
	v_mfma_f32_16x16x32_bf16 v[60:63], v[134:137], v[194:197], v[60:63]
	v_mfma_f32_16x16x32_bf16 v[56:59], v[142:145], v[194:197], v[56:59]
	v_mfma_f32_16x16x32_bf16 v[44:47], v[134:137], v[202:205], v[44:47]
	v_mfma_f32_16x16x32_bf16 v[40:43], v[142:145], v[202:205], v[40:43]
	v_mfma_f32_16x16x32_bf16 v[28:31], v[134:137], v[210:213], v[28:31]
	v_mfma_f32_16x16x32_bf16 v[24:27], v[142:145], v[210:213], v[24:27]
	v_mfma_f32_16x16x32_bf16 v[12:15], v[134:137], v[244:247], v[12:15]
	v_mfma_f32_16x16x32_bf16 v[8:11], v[142:145], v[244:247], v[8:11]
	v_mfma_f32_16x16x32_bf16 v[52:55], v[146:149], v[190:193], v[52:55]
	v_mfma_f32_16x16x32_bf16 v[48:51], v[154:157], v[190:193], v[48:51]
	v_mfma_f32_16x16x32_bf16 v[36:39], v[146:149], v[198:201], v[36:39]
	v_mfma_f32_16x16x32_bf16 v[32:35], v[154:157], v[198:201], v[32:35]
	v_mfma_f32_16x16x32_bf16 v[20:23], v[146:149], v[206:209], v[20:23]
	v_mfma_f32_16x16x32_bf16 v[16:19], v[154:157], v[206:209], v[16:19]
	v_mfma_f32_16x16x32_bf16 v[4:7], v[146:149], v[240:243], v[4:7]
	v_mfma_f32_16x16x32_bf16 v[0:3], v[154:157], v[240:243], v[0:3]
	v_mfma_f32_16x16x32_bf16 v[52:55], v[150:153], v[194:197], v[52:55]
	v_mfma_f32_16x16x32_bf16 v[48:51], v[186:189], v[194:197], v[48:51]
	v_mfma_f32_16x16x32_bf16 v[36:39], v[150:153], v[202:205], v[36:39]
	v_mfma_f32_16x16x32_bf16 v[32:35], v[186:189], v[202:205], v[32:35]
	v_mfma_f32_16x16x32_bf16 v[20:23], v[150:153], v[210:213], v[20:23]
	v_mfma_f32_16x16x32_bf16 v[16:19], v[186:189], v[210:213], v[16:19]
	v_mfma_f32_16x16x32_bf16 v[4:7], v[150:153], v[244:247], v[4:7]
	v_mfma_f32_16x16x32_bf16 v[0:3], v[186:189], v[244:247], v[0:3]
	s_setprio 0
	s_barrier
	s_add_i32 s46, 0, 0x18000
	s_add_i32 s70, 0, 0x1c000
	v_add_u32_e32 v142, s46, v218
	v_add_u32_e32 v168, s70, v218
	ds_read_b128 v[130:133], v142
	ds_read_b128 v[134:137], v142 offset:1024
	ds_read_b128 v[138:141], v142 offset:2048
	ds_read_b128 v[142:145], v142 offset:3072
	ds_read_b128 v[146:149], v168
	ds_read_b128 v[150:153], v168 offset:1024
	ds_read_b128 v[154:157], v168 offset:2048
	ds_read_b128 v[186:189], v168 offset:3072
	v_lshl_add_u64 v[158:159], v[158:159], 0, s[94:95]
	s_mov_b32 m0, s55
	v_lshl_add_u64 v[252:253], v[158:159], 0, v[178:179]
	ds_read_b128 v[190:193], v219 offset:32768
	ds_read_b128 v[194:197], v219 offset:33792
	ds_read_b128 v[198:201], v219 offset:34816
	ds_read_b128 v[202:205], v219 offset:35840
	ds_read_b128 v[206:209], v219 offset:36864
	ds_read_b128 v[210:213], v219 offset:37888
	ds_read_b128 v[240:243], v219 offset:38912
	ds_read_b128 v[244:247], v219 offset:39936
	global_load_lds_dwordx4 v[252:253], off
	v_lshl_add_u64 v[158:159], v[158:159], 0, v[182:183]
	s_mov_b32 m0, s56
	s_nop 0
	global_load_lds_dwordx4 v[158:159], off
	s_waitcnt vmcnt(8)
	s_waitcnt lgkmcnt(0)
	s_barrier
	s_setprio 1
	s_waitcnt lgkmcnt(0)
	v_mfma_f32_16x16x32_bf16 v[120:123], v[130:133], v[190:193], v[120:123]
	v_mfma_f32_16x16x32_bf16 v[124:127], v[138:141], v[190:193], v[124:127]
	v_mfma_f32_16x16x32_bf16 v[108:111], v[130:133], v[198:201], v[108:111]
	v_mfma_f32_16x16x32_bf16 v[104:107], v[138:141], v[198:201], v[104:107]
	v_mfma_f32_16x16x32_bf16 v[92:95], v[130:133], v[206:209], v[92:95]
	v_mfma_f32_16x16x32_bf16 v[88:91], v[138:141], v[206:209], v[88:91]
	v_mfma_f32_16x16x32_bf16 v[76:79], v[130:133], v[240:243], v[76:79]
	v_mfma_f32_16x16x32_bf16 v[72:75], v[138:141], v[240:243], v[72:75]
	v_mfma_f32_16x16x32_bf16 v[120:123], v[134:137], v[194:197], v[120:123]
	v_mfma_f32_16x16x32_bf16 v[124:127], v[142:145], v[194:197], v[124:127]
	v_mfma_f32_16x16x32_bf16 v[108:111], v[134:137], v[202:205], v[108:111]
	v_mfma_f32_16x16x32_bf16 v[104:107], v[142:145], v[202:205], v[104:107]
	v_mfma_f32_16x16x32_bf16 v[92:95], v[134:137], v[210:213], v[92:95]
	v_mfma_f32_16x16x32_bf16 v[88:91], v[142:145], v[210:213], v[88:91]
	v_mfma_f32_16x16x32_bf16 v[76:79], v[134:137], v[244:247], v[76:79]
	v_mfma_f32_16x16x32_bf16 v[72:75], v[142:145], v[244:247], v[72:75]
	v_mfma_f32_16x16x32_bf16 v[116:119], v[146:149], v[190:193], v[116:119]
	v_mfma_f32_16x16x32_bf16 v[112:115], v[154:157], v[190:193], v[112:115]
	v_mfma_f32_16x16x32_bf16 v[100:103], v[146:149], v[198:201], v[100:103]
	v_mfma_f32_16x16x32_bf16 v[96:99], v[154:157], v[198:201], v[96:99]
	v_mfma_f32_16x16x32_bf16 v[84:87], v[146:149], v[206:209], v[84:87]
	v_mfma_f32_16x16x32_bf16 v[80:83], v[154:157], v[206:209], v[80:83]
	v_mfma_f32_16x16x32_bf16 v[68:71], v[146:149], v[240:243], v[68:71]
	v_mfma_f32_16x16x32_bf16 v[64:67], v[154:157], v[240:243], v[64:67]
	v_mfma_f32_16x16x32_bf16 v[116:119], v[150:153], v[194:197], v[116:119]
	v_mfma_f32_16x16x32_bf16 v[112:115], v[186:189], v[194:197], v[112:115]
	v_mfma_f32_16x16x32_bf16 v[100:103], v[150:153], v[202:205], v[100:103]
	v_mfma_f32_16x16x32_bf16 v[96:99], v[186:189], v[202:205], v[96:99]
	v_mfma_f32_16x16x32_bf16 v[84:87], v[150:153], v[210:213], v[84:87]
	v_mfma_f32_16x16x32_bf16 v[80:83], v[186:189], v[210:213], v[80:83]
	v_mfma_f32_16x16x32_bf16 v[68:71], v[150:153], v[244:247], v[68:71]
	v_mfma_f32_16x16x32_bf16 v[64:67], v[186:189], v[244:247], v[64:67]
	s_setprio 0
	s_barrier
; #define PG8_STAGE(bufoff, gbase, voff) do { _Pragma("unroll") for (int _i = 0; _i < 2; ++_i) \
;         __builtin_amdgcn_global_load_lds((const unsigned*)((const char*)(gbase) + (voff)[_i]), (LAS unsigned*)(lds + (bufoff) + ldsw + _i * 8192), 16, 0, 0); } while (0)
; #define PG8_LDA(dst, b, h) do { _Pragma("unroll") for (int m = 0; m < 4; ++m) _Pragma("unroll") for (int k = 0; k < 2; ++k) dst[m][k] = *(const LAS bf16x8*)(lds + PG8_SA(b, h) + aoff + m * 2048 + k * 1024); } while (0)
; #define PG8_MMA(ai, bj, At, Bt) do { __builtin_amdgcn_s_setprio(1); _Pragma("unroll") for (int k = 0; k < 2; ++k) _Pragma("unroll") for (int m = 0; m < 4; ++m) _Pragma("unroll") for (int n = 0; n < 2; ++n) \
;         acc[ai][bj][m][n] = __builtin_amdgcn_mfma_f32_16x16x32_bf16(Bt[n][k], At[m][k], acc[ai][bj][m][n], 0, 0, 0); __builtin_amdgcn_s_setprio(0); } while (0)
; #define PG8_WAIT_V(n) asm volatile("s_waitcnt vmcnt(" #n ")" ::: "memory")
; #define PG8_WAIT_L(n) asm volatile("s_waitcnt lgkmcnt(" #n ")" ::: "memory")
; #define PG8_BAR __builtin_amdgcn_s_barrier()
; #define PG8_SCHED __builtin_amdgcn_sched_barrier(0)
; template <class Epi, bool ALIGN_EPI>
; __device__ __forceinline__ void gemm_phase(LAS unsigned char* lds, const Gemm g, const StaticOrder& S, const Epi& E, const int tid) {
;     ...
;             PG8_LDA(At, 1, 1); PG8_STAGE(PG8_SB(1, 0), b3, voffB); PG8_STAGE(PG8_SB(1, 1), b3 + hB, voffB); PG8_STAGE(PG8_SA(1, 0), a3, voffA);
;             PG8_WAIT_V(8); PG8_WAIT_L(0); PG8_BAR; PG8_MMA(1, 0, At, B0); PG8_MMA(1, 1, At, B1); PG8_BAR; PG8_SCHED;
;         }
	s_add_i32 s46, s46, s52
	v_lshl_add_u64 v[158:159], v[166:167], 0, s[92:93]
	s_mov_b32 m0, s46
	ds_read_b128 v[190:193], v219 offset:49152
	ds_read_b128 v[194:197], v219 offset:50176
	ds_read_b128 v[198:201], v219 offset:51200
	ds_read_b128 v[202:205], v219 offset:52224
	ds_read_b128 v[206:209], v219 offset:53248
	ds_read_b128 v[210:213], v219 offset:54272
	ds_read_b128 v[240:243], v219 offset:55296
	ds_read_b128 v[244:247], v219 offset:56320
	global_load_lds_dwordx4 v[158:159], off
	v_lshl_add_u64 v[158:159], v[214:215], 0, s[92:93]
	s_add_i32 m0, s46, 0x2000
	s_add_i32 s46, s70, s52
	global_load_lds_dwordx4 v[158:159], off
	v_lshl_add_u64 v[158:159], v[220:221], 0, s[92:93]
	s_mov_b32 m0, s46
	s_nop 0
	global_load_lds_dwordx4 v[158:159], off
	v_lshl_add_u64 v[158:159], v[226:227], 0, s[92:93]
	s_add_i32 m0, s46, 0x2000
	s_nop 0
	global_load_lds_dwordx4 v[158:159], off
	v_lshl_add_u64 v[158:159], v[248:249], 0, s[92:93]
	s_mov_b32 m0, s57
	s_nop 0
	global_load_lds_dwordx4 v[158:159], off
	v_lshl_add_u64 v[158:159], v[250:251], 0, s[92:93]
	s_mov_b32 m0, s58
	s_nop 0
	global_load_lds_dwordx4 v[158:159], off
	s_waitcnt vmcnt(8)
	s_waitcnt lgkmcnt(0)
	s_barrier
	s_setprio 1
	s_waitcnt lgkmcnt(0)
	v_mfma_f32_16x16x32_bf16 v[60:63], v[130:133], v[190:193], v[60:63]
	v_mfma_f32_16x16x32_bf16 v[56:59], v[138:141], v[190:193], v[56:59]
	v_mfma_f32_16x16x32_bf16 v[44:47], v[130:133], v[198:201], v[44:47]
	v_mfma_f32_16x16x32_bf16 v[40:43], v[138:141], v[198:201], v[40:43]
	v_mfma_f32_16x16x32_bf16 v[28:31], v[130:133], v[206:209], v[28:31]
	v_mfma_f32_16x16x32_bf16 v[24:27], v[138:141], v[206:209], v[24:27]
	v_mfma_f32_16x16x32_bf16 v[12:15], v[130:133], v[240:243], v[12:15]
	v_mfma_f32_16x16x32_bf16 v[8:11], v[138:141], v[240:243], v[8:11]
	v_mfma_f32_16x16x32_bf16 v[60:63], v[134:137], v[194:197], v[60:63]
	v_mfma_f32_16x16x32_bf16 v[56:59], v[142:145], v[194:197], v[56:59]
	v_mfma_f32_16x16x32_bf16 v[44:47], v[134:137], v[202:205], v[44:47]
	v_mfma_f32_16x16x32_bf16 v[40:43], v[142:145], v[202:205], v[40:43]
	v_mfma_f32_16x16x32_bf16 v[28:31], v[134:137], v[210:213], v[28:31]
	v_mfma_f32_16x16x32_bf16 v[24:27], v[142:145], v[210:213], v[24:27]
	v_mfma_f32_16x16x32_bf16 v[12:15], v[134:137], v[244:247], v[12:15]
	v_mfma_f32_16x16x32_bf16 v[8:11], v[142:145], v[244:247], v[8:11]
	v_mfma_f32_16x16x32_bf16 v[52:55], v[146:149], v[190:193], v[52:55]
	v_mfma_f32_16x16x32_bf16 v[48:51], v[154:157], v[190:193], v[48:51]
	v_mfma_f32_16x16x32_bf16 v[36:39], v[146:149], v[198:201], v[36:39]
	v_mfma_f32_16x16x32_bf16 v[32:35], v[154:157], v[198:201], v[32:35]
	v_mfma_f32_16x16x32_bf16 v[20:23], v[146:149], v[206:209], v[20:23]
	v_mfma_f32_16x16x32_bf16 v[16:19], v[154:157], v[206:209], v[16:19]
	v_mfma_f32_16x16x32_bf16 v[4:7], v[146:149], v[240:243], v[4:7]
	v_mfma_f32_16x16x32_bf16 v[0:3], v[154:157], v[240:243], v[0:3]
	v_mfma_f32_16x16x32_bf16 v[52:55], v[150:153], v[194:197], v[52:55]
	v_mfma_f32_16x16x32_bf16 v[48:51], v[186:189], v[194:197], v[48:51]
	v_mfma_f32_16x16x32_bf16 v[36:39], v[150:153], v[202:205], v[36:39]
	v_mfma_f32_16x16x32_bf16 v[32:35], v[186:189], v[202:205], v[32:35]
	v_mfma_f32_16x16x32_bf16 v[20:23], v[150:153], v[210:213], v[20:23]
	v_mfma_f32_16x16x32_bf16 v[16:19], v[186:189], v[210:213], v[16:19]
	v_mfma_f32_16x16x32_bf16 v[4:7], v[150:153], v[244:247], v[4:7]
	v_mfma_f32_16x16x32_bf16 v[0:3], v[186:189], v[244:247], v[0:3]
	s_setprio 0
	s_barrier
	s_add_u32 s12, s12, 0x100
	s_addc_u32 s13, s13, 0
	v_lshl_add_u64 v[128:129], v[128:129], 0, s[80:81]
	s_cmp_ge_u32 s47, s48
	s_mov_b32 s46, s47
	s_cbranch_scc0 .LBB0_236
	v_readlane_b32 s70, v255, 47
	s_mov_b32 s72, 0x40000
	v_readlane_b32 s71, v255, 48

; #define PG8_STAGE(bufoff, gbase, voff) do { _Pragma("unroll") for (int _i = 0; _i < 2; ++_i) \
;         __builtin_amdgcn_global_load_lds((const unsigned*)((const char*)(gbase) + (voff)[_i]), (LAS unsigned*)(lds + (bufoff) + ldsw + _i * 8192), 16, 0, 0); } while (0)
; #define PG8_LDA(dst, b, h) do { _Pragma("unroll") for (int m = 0; m < 4; ++m) _Pragma("unroll") for (int k = 0; k < 2; ++k) dst[m][k] = *(const LAS bf16x8*)(lds + PG8_SA(b, h) + aoff + m * 2048 + k * 1024); } while (0)
; #define PG8_LDB(dst, b, h) do { _Pragma("unroll") for (int n = 0; n < 2; ++n) _Pragma("unroll") for (int k = 0; k < 2; ++k) dst[n][k] = *(const LAS bf16x8*)(lds + PG8_SB(b, h) + boff + n * 2048 + k * 1024); } while (0)
; #define PG8_MMA(ai, bj, At, Bt) do { __builtin_amdgcn_s_setprio(1); _Pragma("unroll") for (int k = 0; k < 2; ++k) _Pragma("unroll") for (int m = 0; m < 4; ++m) _Pragma("unroll") for (int n = 0; n < 2; ++n) \
;         acc[ai][bj][m][n] = __builtin_amdgcn_mfma_f32_16x16x32_bf16(Bt[n][k], At[m][k], acc[ai][bj][m][n], 0, 0, 0); __builtin_amdgcn_s_setprio(0); } while (0)
; #define PG8_WAIT_V(n) asm volatile("s_waitcnt vmcnt(" #n ")" ::: "memory")
; #define PG8_WAIT_L(n) asm volatile("s_waitcnt lgkmcnt(" #n ")" ::: "memory")
; #define PG8_BAR __builtin_amdgcn_s_barrier()
; #define PG8_SCHED __builtin_amdgcn_sched_barrier(0)
; template <class Epi, bool ALIGN_EPI>
; __device__ __forceinline__ void gemm_phase(LAS unsigned char* lds, const Gemm g, const StaticOrder& S, const Epi& E, const int tid) {
;     ...
;             const bool last = (t == nt - 2);
;             const char* a1 = cA + (size_t)(t + 1) * kstep;
;             const char* a2 = last ? nA : cA + (size_t)(t + 2) * kstep; const char* b2 = last ? nB : cB + (size_t)(t + 2) * kstep;
;             const char* a3 = a2 + kstep; const char* b3 = b2 + kstep;
;             PG8_LDB(B0, 0, 0); PG8_LDB(B1, 0, 1); PG8_SCHED; PG8_LDA(At, 0, 0); PG8_STAGE(PG8_SA(1, 1), a1 + hA, voffA);
;             PG8_WAIT_V(8); PG8_WAIT_L(0); PG8_BAR; PG8_MMA(0, 0, At, B0); PG8_MMA(0, 1, At, B1); PG8_BAR; PG8_SCHED;
;             PG8_LDA(At, 0, 1); PG8_STAGE(PG8_SB(0, 0), b2, voffB); PG8_STAGE(PG8_SB(0, 1), b2 + hB, voffB); PG8_STAGE(PG8_SA(0, 0), a2, voffA);
;             PG8_WAIT_V(8); PG8_WAIT_L(0); PG8_BAR; PG8_MMA(1, 0, At, B0); PG8_MMA(1, 1, At, B1); PG8_BAR; PG8_SCHED;
.LBB0_274:
	s_add_i32 s15, s14, 2
	s_cmp_eq_u32 s57, s14
	s_cselect_b64 vcc, -1, 0
	s_cselect_b32 s69, s13, s11
	s_cselect_b32 s68, s12, s10
	s_add_i32 s14, 0, 0x14000
	v_lshl_add_u64 v[130:131], v[128:129], 0, s[92:93]
	v_add_u32_e32 v142, s33, v239
	v_add_u32_e32 v158, s14, v239
	v_cndmask_b32_e32 v167, v131, v191, vcc
	v_cndmask_b32_e32 v166, v130, v190, vcc
	ds_read_b128 v[130:133], v142
	ds_read_b128 v[134:137], v142 offset:1024
	ds_read_b128 v[138:141], v142 offset:2048
	ds_read_b128 v[142:145], v142 offset:3072
	ds_read_b128 v[146:149], v158
	ds_read_b128 v[150:153], v158 offset:1024
	ds_read_b128 v[154:157], v158 offset:2048
	ds_read_b128 v[158:161], v158 offset:3072
	v_lshl_add_u64 v[220:221], v[128:129], 0, v[186:187]
	s_add_i32 m0, s51, 0xc000
	ds_read_b128 v[162:165], v171
	ds_read_b128 v[192:195], v171 offset:1024
	ds_read_b128 v[196:199], v171 offset:2048
	ds_read_b128 v[200:203], v171 offset:3072
	ds_read_b128 v[204:207], v171 offset:4096
	ds_read_b128 v[208:211], v171 offset:5120
	ds_read_b128 v[212:215], v171 offset:6144
	ds_read_b128 v[216:219], v171 offset:7168
	global_load_lds_dwordx4 v[220:221], off
	v_lshl_add_u64 v[220:221], v[128:129], 0, v[188:189]
	s_add_i32 m0, s51, 0xe000
	s_nop 0
	global_load_lds_dwordx4 v[220:221], off
	s_waitcnt vmcnt(8)
	s_waitcnt lgkmcnt(0)
	s_barrier
	s_setprio 1
	s_waitcnt lgkmcnt(0)
	v_mfma_f32_16x16x32_bf16 v[124:127], v[130:133], v[162:165], v[124:127]
	v_mfma_f32_16x16x32_bf16 v[120:123], v[138:141], v[162:165], v[120:123]
	v_mfma_f32_16x16x32_bf16 v[108:111], v[130:133], v[196:199], v[108:111]
	v_mfma_f32_16x16x32_bf16 v[104:107], v[138:141], v[196:199], v[104:107]
	v_mfma_f32_16x16x32_bf16 v[92:95], v[130:133], v[204:207], v[92:95]
	v_mfma_f32_16x16x32_bf16 v[88:91], v[138:141], v[204:207], v[88:91]
	v_mfma_f32_16x16x32_bf16 v[76:79], v[130:133], v[212:215], v[76:79]
	v_mfma_f32_16x16x32_bf16 v[72:75], v[138:141], v[212:215], v[72:75]
	v_mfma_f32_16x16x32_bf16 v[124:127], v[134:137], v[192:195], v[124:127]
	v_mfma_f32_16x16x32_bf16 v[120:123], v[142:145], v[192:195], v[120:123]
	v_mfma_f32_16x16x32_bf16 v[108:111], v[134:137], v[200:203], v[108:111]
	v_mfma_f32_16x16x32_bf16 v[104:107], v[142:145], v[200:203], v[104:107]
	v_mfma_f32_16x16x32_bf16 v[92:95], v[134:137], v[208:211], v[92:95]
	v_mfma_f32_16x16x32_bf16 v[88:91], v[142:145], v[208:211], v[88:91]
	v_mfma_f32_16x16x32_bf16 v[76:79], v[134:137], v[216:219], v[76:79]
	v_mfma_f32_16x16x32_bf16 v[72:75], v[142:145], v[216:219], v[72:75]
	v_mfma_f32_16x16x32_bf16 v[116:119], v[146:149], v[162:165], v[116:119]
	v_mfma_f32_16x16x32_bf16 v[112:115], v[154:157], v[162:165], v[112:115]
	v_mfma_f32_16x16x32_bf16 v[100:103], v[146:149], v[196:199], v[100:103]
	v_mfma_f32_16x16x32_bf16 v[96:99], v[154:157], v[196:199], v[96:99]
	v_mfma_f32_16x16x32_bf16 v[84:87], v[146:149], v[204:207], v[84:87]
	v_mfma_f32_16x16x32_bf16 v[80:83], v[154:157], v[204:207], v[80:83]
	v_mfma_f32_16x16x32_bf16 v[68:71], v[146:149], v[212:215], v[68:71]
	v_mfma_f32_16x16x32_bf16 v[64:67], v[154:157], v[212:215], v[64:67]
	v_mfma_f32_16x16x32_bf16 v[116:119], v[150:153], v[192:195], v[116:119]
	v_mfma_f32_16x16x32_bf16 v[112:115], v[158:161], v[192:195], v[112:115]
	v_mfma_f32_16x16x32_bf16 v[100:103], v[150:153], v[200:203], v[100:103]
	v_mfma_f32_16x16x32_bf16 v[96:99], v[158:161], v[200:203], v[96:99]
	v_mfma_f32_16x16x32_bf16 v[84:87], v[150:153], v[208:211], v[84:87]
	v_mfma_f32_16x16x32_bf16 v[80:83], v[158:161], v[208:211], v[80:83]
	v_mfma_f32_16x16x32_bf16 v[68:71], v[150:153], v[216:219], v[68:71]
	v_mfma_f32_16x16x32_bf16 v[64:67], v[158:161], v[216:219], v[64:67]
	s_setprio 0
	s_barrier
	s_add_i32 s70, s33, s47
	v_lshl_add_u64 v[220:221], s[68:69], 0, v[180:181]
	s_mov_b32 m0, s70
	ds_read_b128 v[162:165], v171 offset:16384
	ds_read_b128 v[192:195], v171 offset:17408
	ds_read_b128 v[196:199], v171 offset:18432
	ds_read_b128 v[200:203], v171 offset:19456
	ds_read_b128 v[204:207], v171 offset:20480
	ds_read_b128 v[208:211], v171 offset:21504
	ds_read_b128 v[212:215], v171 offset:22528
	ds_read_b128 v[216:219], v171 offset:23552
	global_load_lds_dwordx4 v[220:221], off
	s_add_i32 m0, s70, 0x2000
	v_lshl_add_u64 v[226:227], s[68:69], 0, v[184:185]
	s_add_u32 s68, s68, s49
	s_addc_u32 s69, s69, 0
	s_add_i32 s14, s14, s47
	global_load_lds_dwordx4 v[226:227], off
	v_lshl_add_u64 v[240:241], s[68:69], 0, v[180:181]
	s_mov_b32 m0, s14
	v_lshl_add_u64 v[242:243], s[68:69], 0, v[184:185]
	global_load_lds_dwordx4 v[240:241], off
	s_add_i32 m0, s14, 0x2000
	v_lshl_add_u64 v[244:245], v[166:167], 0, v[178:179]
	global_load_lds_dwordx4 v[242:243], off
	s_mov_b32 m0, s51
	v_lshl_add_u64 v[246:247], v[166:167], 0, v[182:183]
	global_load_lds_dwordx4 v[244:245], off
	s_mov_b32 m0, s52
	s_nop 0
	global_load_lds_dwordx4 v[246:247], off
	s_waitcnt vmcnt(8)
	s_waitcnt lgkmcnt(0)
	s_barrier
; #define PG8_STAGE(bufoff, gbase, voff) do { _Pragma("unroll") for (int _i = 0; _i < 2; ++_i) \
;         __builtin_amdgcn_global_load_lds((const unsigned*)((const char*)(gbase) + (voff)[_i]), (LAS unsigned*)(lds + (bufoff) + ldsw + _i * 8192), 16, 0, 0); } while (0)
; #define PG8_LDA(dst, b, h) do { _Pragma("unroll") for (int m = 0; m < 4; ++m) _Pragma("unroll") for (int k = 0; k < 2; ++k) dst[m][k] = *(const LAS bf16x8*)(lds + PG8_SA(b, h) + aoff + m * 2048 + k * 1024); } while (0)
; #define PG8_LDB(dst, b, h) do { _Pragma("unroll") for (int n = 0; n < 2; ++n) _Pragma("unroll") for (int k = 0; k < 2; ++k) dst[n][k] = *(const LAS bf16x8*)(lds + PG8_SB(b, h) + boff + n * 2048 + k * 1024); } while (0)
; #define PG8_MMA(ai, bj, At, Bt) do { __builtin_amdgcn_s_setprio(1); _Pragma("unroll") for (int k = 0; k < 2; ++k) _Pragma("unroll") for (int m = 0; m < 4; ++m) _Pragma("unroll") for (int n = 0; n < 2; ++n) \
;         acc[ai][bj][m][n] = __builtin_amdgcn_mfma_f32_16x16x32_bf16(Bt[n][k], At[m][k], acc[ai][bj][m][n], 0, 0, 0); __builtin_amdgcn_s_setprio(0); } while (0)
; #define PG8_WAIT_V(n) asm volatile("s_waitcnt vmcnt(" #n ")" ::: "memory")
; #define PG8_WAIT_L(n) asm volatile("s_waitcnt lgkmcnt(" #n ")" ::: "memory")
; #define PG8_BAR __builtin_amdgcn_s_barrier()
; #define PG8_SCHED __builtin_amdgcn_sched_barrier(0)
; template <class Epi, bool ALIGN_EPI>
; __device__ __forceinline__ void gemm_phase(LAS unsigned char* lds, const Gemm g, const StaticOrder& S, const Epi& E, const int tid) {
;     ...
;             PG8_WAIT_V(8); PG8_WAIT_L(0); PG8_BAR; PG8_MMA(1, 0, At, B0); PG8_MMA(1, 1, At, B1); PG8_BAR; PG8_SCHED;
;             PG8_LDB(B0, 1, 0); PG8_LDB(B1, 1, 1); PG8_SCHED; PG8_LDA(At, 1, 0); PG8_STAGE(PG8_SA(0, 1), a2 + hA, voffA);
;             PG8_WAIT_V(8); PG8_WAIT_L(0); PG8_BAR; PG8_MMA(0, 0, At, B0); PG8_MMA(0, 1, At, B1); PG8_BAR; PG8_SCHED;
	s_setprio 1
	s_waitcnt lgkmcnt(0)
	v_mfma_f32_16x16x32_bf16 v[60:63], v[130:133], v[162:165], v[60:63]
	v_mfma_f32_16x16x32_bf16 v[56:59], v[138:141], v[162:165], v[56:59]
	v_mfma_f32_16x16x32_bf16 v[44:47], v[130:133], v[196:199], v[44:47]
	v_mfma_f32_16x16x32_bf16 v[40:43], v[138:141], v[196:199], v[40:43]
	v_mfma_f32_16x16x32_bf16 v[28:31], v[130:133], v[204:207], v[28:31]
	v_mfma_f32_16x16x32_bf16 v[24:27], v[138:141], v[204:207], v[24:27]
	v_mfma_f32_16x16x32_bf16 v[12:15], v[130:133], v[212:215], v[12:15]
	v_mfma_f32_16x16x32_bf16 v[8:11], v[138:141], v[212:215], v[8:11]
	v_mfma_f32_16x16x32_bf16 v[60:63], v[134:137], v[192:195], v[60:63]
	v_mfma_f32_16x16x32_bf16 v[56:59], v[142:145], v[192:195], v[56:59]
	v_mfma_f32_16x16x32_bf16 v[44:47], v[134:137], v[200:203], v[44:47]
	v_mfma_f32_16x16x32_bf16 v[40:43], v[142:145], v[200:203], v[40:43]
	v_mfma_f32_16x16x32_bf16 v[28:31], v[134:137], v[208:211], v[28:31]
	v_mfma_f32_16x16x32_bf16 v[24:27], v[142:145], v[208:211], v[24:27]
	v_mfma_f32_16x16x32_bf16 v[12:15], v[134:137], v[216:219], v[12:15]
	v_mfma_f32_16x16x32_bf16 v[8:11], v[142:145], v[216:219], v[8:11]
	v_mfma_f32_16x16x32_bf16 v[52:55], v[146:149], v[162:165], v[52:55]
	v_mfma_f32_16x16x32_bf16 v[48:51], v[154:157], v[162:165], v[48:51]
	v_mfma_f32_16x16x32_bf16 v[36:39], v[146:149], v[196:199], v[36:39]
	v_mfma_f32_16x16x32_bf16 v[32:35], v[154:157], v[196:199], v[32:35]
	v_mfma_f32_16x16x32_bf16 v[20:23], v[146:149], v[204:207], v[20:23]
	v_mfma_f32_16x16x32_bf16 v[16:19], v[154:157], v[204:207], v[16:19]
	v_mfma_f32_16x16x32_bf16 v[4:7], v[146:149], v[212:215], v[4:7]
	v_mfma_f32_16x16x32_bf16 v[0:3], v[154:157], v[212:215], v[0:3]
	v_mfma_f32_16x16x32_bf16 v[52:55], v[150:153], v[192:195], v[52:55]
	v_mfma_f32_16x16x32_bf16 v[48:51], v[158:161], v[192:195], v[48:51]
	v_mfma_f32_16x16x32_bf16 v[36:39], v[150:153], v[200:203], v[36:39]
	v_mfma_f32_16x16x32_bf16 v[32:35], v[158:161], v[200:203], v[32:35]
	v_mfma_f32_16x16x32_bf16 v[20:23], v[150:153], v[208:211], v[20:23]
	v_mfma_f32_16x16x32_bf16 v[16:19], v[158:161], v[208:211], v[16:19]
	v_mfma_f32_16x16x32_bf16 v[4:7], v[150:153], v[216:219], v[4:7]
	v_mfma_f32_16x16x32_bf16 v[0:3], v[158:161], v[216:219], v[0:3]
	s_setprio 0
	s_barrier
	s_add_i32 s14, 0, 0x18000
	s_add_i32 s68, 0, 0x1c000
	v_add_u32_e32 v142, s14, v239
	v_add_u32_e32 v158, s68, v239
	ds_read_b128 v[130:133], v142
	ds_read_b128 v[134:137], v142 offset:1024
	ds_read_b128 v[138:141], v142 offset:2048
	ds_read_b128 v[142:145], v142 offset:3072
	ds_read_b128 v[146:149], v158
	ds_read_b128 v[150:153], v158 offset:1024
	ds_read_b128 v[154:157], v158 offset:2048
	ds_read_b128 v[158:161], v158 offset:3072
	v_lshl_add_u64 v[166:167], v[166:167], 0, s[94:95]
	s_mov_b32 m0, s53
	v_lshl_add_u64 v[248:249], v[166:167], 0, v[178:179]
	ds_read_b128 v[162:165], v171 offset:32768
	ds_read_b128 v[192:195], v171 offset:33792
	ds_read_b128 v[196:199], v171 offset:34816
	ds_read_b128 v[200:203], v171 offset:35840
	ds_read_b128 v[204:207], v171 offset:36864
	ds_read_b128 v[208:211], v171 offset:37888
	ds_read_b128 v[212:215], v171 offset:38912
	ds_read_b128 v[216:219], v171 offset:39936
	global_load_lds_dwordx4 v[248:249], off
	v_lshl_add_u64 v[166:167], v[166:167], 0, v[182:183]
	s_mov_b32 m0, s54
	s_nop 0
	global_load_lds_dwordx4 v[166:167], off
	s_waitcnt vmcnt(8)
	s_waitcnt lgkmcnt(0)
	s_barrier
	s_setprio 1
	s_waitcnt lgkmcnt(0)
	v_mfma_f32_16x16x32_bf16 v[124:127], v[130:133], v[162:165], v[124:127]
	v_mfma_f32_16x16x32_bf16 v[120:123], v[138:141], v[162:165], v[120:123]
	v_mfma_f32_16x16x32_bf16 v[108:111], v[130:133], v[196:199], v[108:111]
	v_mfma_f32_16x16x32_bf16 v[104:107], v[138:141], v[196:199], v[104:107]
	v_mfma_f32_16x16x32_bf16 v[92:95], v[130:133], v[204:207], v[92:95]
	v_mfma_f32_16x16x32_bf16 v[88:91], v[138:141], v[204:207], v[88:91]
	v_mfma_f32_16x16x32_bf16 v[76:79], v[130:133], v[212:215], v[76:79]
	v_mfma_f32_16x16x32_bf16 v[72:75], v[138:141], v[212:215], v[72:75]
	v_mfma_f32_16x16x32_bf16 v[124:127], v[134:137], v[192:195], v[124:127]
	v_mfma_f32_16x16x32_bf16 v[120:123], v[142:145], v[192:195], v[120:123]
	v_mfma_f32_16x16x32_bf16 v[108:111], v[134:137], v[200:203], v[108:111]
	v_mfma_f32_16x16x32_bf16 v[104:107], v[142:145], v[200:203], v[104:107]
	v_mfma_f32_16x16x32_bf16 v[92:95], v[134:137], v[208:211], v[92:95]
	v_mfma_f32_16x16x32_bf16 v[88:91], v[142:145], v[208:211], v[88:91]
	v_mfma_f32_16x16x32_bf16 v[76:79], v[134:137], v[216:219], v[76:79]
	v_mfma_f32_16x16x32_bf16 v[72:75], v[142:145], v[216:219], v[72:75]
	v_mfma_f32_16x16x32_bf16 v[116:119], v[146:149], v[162:165], v[116:119]
	v_mfma_f32_16x16x32_bf16 v[112:115], v[154:157], v[162:165], v[112:115]
	v_mfma_f32_16x16x32_bf16 v[100:103], v[146:149], v[196:199], v[100:103]
	v_mfma_f32_16x16x32_bf16 v[96:99], v[154:157], v[196:199], v[96:99]
	v_mfma_f32_16x16x32_bf16 v[84:87], v[146:149], v[204:207], v[84:87]
	v_mfma_f32_16x16x32_bf16 v[80:83], v[154:157], v[204:207], v[80:83]
	v_mfma_f32_16x16x32_bf16 v[68:71], v[146:149], v[212:215], v[68:71]
	v_mfma_f32_16x16x32_bf16 v[64:67], v[154:157], v[212:215], v[64:67]
	v_mfma_f32_16x16x32_bf16 v[116:119], v[150:153], v[192:195], v[116:119]
	v_mfma_f32_16x16x32_bf16 v[112:115], v[158:161], v[192:195], v[112:115]
	v_mfma_f32_16x16x32_bf16 v[100:103], v[150:153], v[200:203], v[100:103]
	v_mfma_f32_16x16x32_bf16 v[96:99], v[158:161], v[200:203], v[96:99]
	v_mfma_f32_16x16x32_bf16 v[84:87], v[150:153], v[208:211], v[84:87]
	v_mfma_f32_16x16x32_bf16 v[80:83], v[158:161], v[208:211], v[80:83]
	v_mfma_f32_16x16x32_bf16 v[68:71], v[150:153], v[216:219], v[68:71]
	v_mfma_f32_16x16x32_bf16 v[64:67], v[158:161], v[216:219], v[64:67]
	s_setprio 0
	s_barrier
; #define PG8_STAGE(bufoff, gbase, voff) do { _Pragma("unroll") for (int _i = 0; _i < 2; ++_i) \
;         __builtin_amdgcn_global_load_lds((const unsigned*)((const char*)(gbase) + (voff)[_i]), (LAS unsigned*)(lds + (bufoff) + ldsw + _i * 8192), 16, 0, 0); } while (0)
; #define PG8_LDA(dst, b, h) do { _Pragma("unroll") for (int m = 0; m < 4; ++m) _Pragma("unroll") for (int k = 0; k < 2; ++k) dst[m][k] = *(const LAS bf16x8*)(lds + PG8_SA(b, h) + aoff + m * 2048 + k * 1024); } while (0)
; #define PG8_MMA(ai, bj, At, Bt) do { __builtin_amdgcn_s_setprio(1); _Pragma("unroll") for (int k = 0; k < 2; ++k) _Pragma("unroll") for (int m = 0; m < 4; ++m) _Pragma("unroll") for (int n = 0; n < 2; ++n) \
;         acc[ai][bj][m][n] = __builtin_amdgcn_mfma_f32_16x16x32_bf16(Bt[n][k], At[m][k], acc[ai][bj][m][n], 0, 0, 0); __builtin_amdgcn_s_setprio(0); } while (0)
; #define PG8_WAIT_V(n) asm volatile("s_waitcnt vmcnt(" #n ")" ::: "memory")
; #define PG8_WAIT_L(n) asm volatile("s_waitcnt lgkmcnt(" #n ")" ::: "memory")
; #define PG8_BAR __builtin_amdgcn_s_barrier()
; #define PG8_SCHED __builtin_amdgcn_sched_barrier(0)
; template <class Epi, bool ALIGN_EPI>
; __device__ __forceinline__ void gemm_phase(LAS unsigned char* lds, const Gemm g, const StaticOrder& S, const Epi& E, const int tid) {
;     ...
;             PG8_LDA(At, 1, 1); PG8_STAGE(PG8_SB(1, 0), b3, voffB); PG8_STAGE(PG8_SB(1, 1), b3 + hB, voffB); PG8_STAGE(PG8_SA(1, 0), a3, voffA);
;             PG8_WAIT_V(8); PG8_WAIT_L(0); PG8_BAR; PG8_MMA(1, 0, At, B0); PG8_MMA(1, 1, At, B1); PG8_BAR; PG8_SCHED;
;         }
	s_add_i32 s14, s14, s47
	v_lshl_add_u64 v[166:167], v[220:221], 0, s[92:93]
	s_mov_b32 m0, s14
	ds_read_b128 v[162:165], v171 offset:49152
	ds_read_b128 v[192:195], v171 offset:50176
	ds_read_b128 v[196:199], v171 offset:51200
	ds_read_b128 v[200:203], v171 offset:52224
	ds_read_b128 v[204:207], v171 offset:53248
	ds_read_b128 v[208:211], v171 offset:54272
	ds_read_b128 v[212:215], v171 offset:55296
	ds_read_b128 v[216:219], v171 offset:56320
	global_load_lds_dwordx4 v[166:167], off
	v_lshl_add_u64 v[166:167], v[226:227], 0, s[92:93]
	s_add_i32 m0, s14, 0x2000
	s_add_i32 s14, s68, s47
	global_load_lds_dwordx4 v[166:167], off
	v_lshl_add_u64 v[166:167], v[240:241], 0, s[92:93]
	s_mov_b32 m0, s14
	s_nop 0
	global_load_lds_dwordx4 v[166:167], off
	v_lshl_add_u64 v[166:167], v[242:243], 0, s[92:93]
	s_add_i32 m0, s14, 0x2000
	s_nop 0
	global_load_lds_dwordx4 v[166:167], off
	v_lshl_add_u64 v[166:167], v[244:245], 0, s[92:93]
	s_mov_b32 m0, s55
	s_nop 0
	global_load_lds_dwordx4 v[166:167], off
	v_lshl_add_u64 v[166:167], v[246:247], 0, s[92:93]
	s_mov_b32 m0, s56
	s_nop 0
	global_load_lds_dwordx4 v[166:167], off
	s_waitcnt vmcnt(8)
	s_waitcnt lgkmcnt(0)
	s_barrier
	s_setprio 1
	s_waitcnt lgkmcnt(0)
	v_mfma_f32_16x16x32_bf16 v[60:63], v[130:133], v[162:165], v[60:63]
	v_mfma_f32_16x16x32_bf16 v[56:59], v[138:141], v[162:165], v[56:59]
	v_mfma_f32_16x16x32_bf16 v[44:47], v[130:133], v[196:199], v[44:47]
	v_mfma_f32_16x16x32_bf16 v[40:43], v[138:141], v[196:199], v[40:43]
	v_mfma_f32_16x16x32_bf16 v[28:31], v[130:133], v[204:207], v[28:31]
	v_mfma_f32_16x16x32_bf16 v[24:27], v[138:141], v[204:207], v[24:27]
	v_mfma_f32_16x16x32_bf16 v[12:15], v[130:133], v[212:215], v[12:15]
	v_mfma_f32_16x16x32_bf16 v[8:11], v[138:141], v[212:215], v[8:11]
	v_mfma_f32_16x16x32_bf16 v[60:63], v[134:137], v[192:195], v[60:63]
	v_mfma_f32_16x16x32_bf16 v[56:59], v[142:145], v[192:195], v[56:59]
	v_mfma_f32_16x16x32_bf16 v[44:47], v[134:137], v[200:203], v[44:47]
	v_mfma_f32_16x16x32_bf16 v[40:43], v[142:145], v[200:203], v[40:43]
	v_mfma_f32_16x16x32_bf16 v[28:31], v[134:137], v[208:211], v[28:31]
	v_mfma_f32_16x16x32_bf16 v[24:27], v[142:145], v[208:211], v[24:27]
	v_mfma_f32_16x16x32_bf16 v[12:15], v[134:137], v[216:219], v[12:15]
	v_mfma_f32_16x16x32_bf16 v[8:11], v[142:145], v[216:219], v[8:11]
	v_mfma_f32_16x16x32_bf16 v[52:55], v[146:149], v[162:165], v[52:55]
	v_mfma_f32_16x16x32_bf16 v[48:51], v[154:157], v[162:165], v[48:51]
	v_mfma_f32_16x16x32_bf16 v[36:39], v[146:149], v[196:199], v[36:39]
	v_mfma_f32_16x16x32_bf16 v[32:35], v[154:157], v[196:199], v[32:35]
	v_mfma_f32_16x16x32_bf16 v[20:23], v[146:149], v[204:207], v[20:23]
	v_mfma_f32_16x16x32_bf16 v[16:19], v[154:157], v[204:207], v[16:19]
	v_mfma_f32_16x16x32_bf16 v[4:7], v[146:149], v[212:215], v[4:7]
	v_mfma_f32_16x16x32_bf16 v[0:3], v[154:157], v[212:215], v[0:3]
	v_mfma_f32_16x16x32_bf16 v[52:55], v[150:153], v[192:195], v[52:55]
	v_mfma_f32_16x16x32_bf16 v[48:51], v[158:161], v[192:195], v[48:51]
	v_mfma_f32_16x16x32_bf16 v[36:39], v[150:153], v[200:203], v[36:39]
	v_mfma_f32_16x16x32_bf16 v[32:35], v[158:161], v[200:203], v[32:35]
	v_mfma_f32_16x16x32_bf16 v[20:23], v[150:153], v[208:211], v[20:23]
	v_mfma_f32_16x16x32_bf16 v[16:19], v[158:161], v[208:211], v[16:19]
	v_mfma_f32_16x16x32_bf16 v[4:7], v[150:153], v[216:219], v[4:7]
	v_mfma_f32_16x16x32_bf16 v[0:3], v[158:161], v[216:219], v[0:3]
	s_setprio 0
	s_barrier
	s_add_u32 s10, s10, 0x100
	s_addc_u32 s11, s11, 0
	v_lshl_add_u64 v[128:129], v[128:129], 0, s[80:81]
	s_cmp_ge_u32 s15, s48
	s_mov_b32 s14, s15
	s_cbranch_scc0 .LBB0_274
	s_mov_b64 s[70:71], s[90:91]

; #define PG8_STAGE(bufoff, gbase, voff) do { _Pragma("unroll") for (int _i = 0; _i < 2; ++_i) \
;         __builtin_amdgcn_global_load_lds((const unsigned*)((const char*)(gbase) + (voff)[_i]), (LAS unsigned*)(lds + (bufoff) + ldsw + _i * 8192), 16, 0, 0); } while (0)
; #define PG8_LDA(dst, b, h) do { _Pragma("unroll") for (int m = 0; m < 4; ++m) _Pragma("unroll") for (int k = 0; k < 2; ++k) dst[m][k] = *(const LAS bf16x8*)(lds + PG8_SA(b, h) + aoff + m * 2048 + k * 1024); } while (0)
; #define PG8_LDB(dst, b, h) do { _Pragma("unroll") for (int n = 0; n < 2; ++n) _Pragma("unroll") for (int k = 0; k < 2; ++k) dst[n][k] = *(const LAS bf16x8*)(lds + PG8_SB(b, h) + boff + n * 2048 + k * 1024); } while (0)
; #define PG8_MMA(ai, bj, At, Bt) do { __builtin_amdgcn_s_setprio(1); _Pragma("unroll") for (int k = 0; k < 2; ++k) _Pragma("unroll") for (int m = 0; m < 4; ++m) _Pragma("unroll") for (int n = 0; n < 2; ++n) \
;         acc[ai][bj][m][n] = __builtin_amdgcn_mfma_f32_16x16x32_bf16(Bt[n][k], At[m][k], acc[ai][bj][m][n], 0, 0, 0); __builtin_amdgcn_s_setprio(0); } while (0)
; #define PG8_WAIT_V(n) asm volatile("s_waitcnt vmcnt(" #n ")" ::: "memory")
; #define PG8_WAIT_L(n) asm volatile("s_waitcnt lgkmcnt(" #n ")" ::: "memory")
; #define PG8_BAR __builtin_amdgcn_s_barrier()
; #define PG8_SCHED __builtin_amdgcn_sched_barrier(0)
; template <class Epi, bool ALIGN_EPI>
; __device__ __forceinline__ void gemm_phase(LAS unsigned char* lds, const Gemm g, const StaticOrder& S, const Epi& E, const int tid) {
;     ...
;             const bool last = (t == nt - 2);
;             const char* a1 = cA + (size_t)(t + 1) * kstep;
;             const char* a2 = last ? nA : cA + (size_t)(t + 2) * kstep; const char* b2 = last ? nB : cB + (size_t)(t + 2) * kstep;
;             const char* a3 = a2 + kstep; const char* b3 = b2 + kstep;
;             PG8_LDB(B0, 0, 0); PG8_LDB(B1, 0, 1); PG8_SCHED; PG8_LDA(At, 0, 0); PG8_STAGE(PG8_SA(1, 1), a1 + hA, voffA);
;             PG8_WAIT_V(8); PG8_WAIT_L(0); PG8_BAR; PG8_MMA(0, 0, At, B0); PG8_MMA(0, 1, At, B1); PG8_BAR; PG8_SCHED;
;             PG8_LDA(At, 0, 1); PG8_STAGE(PG8_SB(0, 0), b2, voffB); PG8_STAGE(PG8_SB(0, 1), b2 + hB, voffB); PG8_STAGE(PG8_SA(0, 0), a2, voffA);
;             PG8_WAIT_V(8); PG8_WAIT_L(0); PG8_BAR; PG8_MMA(1, 0, At, B0); PG8_MMA(1, 1, At, B1); PG8_BAR; PG8_SCHED;
.LBB0_308:
	s_add_i32 s11, s10, 2
	s_cmp_eq_u32 s58, s10
	v_lshl_add_u64 v[146:147], v[142:143], 0, s[92:93]
	s_cselect_b64 vcc, -1, 0
	v_add_u32_e32 v150, s33, v151
	s_add_i32 s10, 0, 0x14000
	v_cndmask_b32_e32 v167, v147, v139, vcc
	v_cndmask_b32_e32 v166, v146, v138, vcc
	ds_read_b128 v[146:149], v150
	ds_read_b128 v[154:157], v150 offset:1024
	ds_read_b128 v[158:161], v150 offset:2048
	ds_read_b128 v[162:165], v150 offset:3072
	v_add_u32_e32 v150, s10, v151
	ds_read_b128 v[176:179], v150
	ds_read_b128 v[180:183], v150 offset:1024
	ds_read_b128 v[184:187], v150 offset:2048
	ds_read_b128 v[188:191], v150 offset:3072
	v_cndmask_b32_e32 v221, v145, v141, vcc
	v_cndmask_b32_e32 v220, v144, v140, vcc
	v_lshl_add_u64 v[226:227], v[142:143], 0, v[134:135]
	s_add_i32 m0, s51, 0xc000
	ds_read_b128 v[192:195], v153
	ds_read_b128 v[196:199], v153 offset:1024
	ds_read_b128 v[200:203], v153 offset:2048
	ds_read_b128 v[204:207], v153 offset:3072
	ds_read_b128 v[208:211], v153 offset:4096
	ds_read_b128 v[212:215], v153 offset:5120
	ds_read_b128 v[216:219], v153 offset:6144
	ds_read_b128 v[240:243], v153 offset:7168
	global_load_lds_dwordx4 v[226:227], off
	v_lshl_add_u64 v[226:227], v[142:143], 0, v[136:137]
	s_add_i32 m0, s51, 0xe000
	s_nop 0
	global_load_lds_dwordx4 v[226:227], off
	s_waitcnt vmcnt(8)
	s_waitcnt lgkmcnt(0)
	s_barrier
	s_setprio 1
	s_waitcnt lgkmcnt(0)
	v_mfma_f32_16x16x32_bf16 v[120:123], v[146:149], v[192:195], v[120:123]
	v_mfma_f32_16x16x32_bf16 v[112:115], v[158:161], v[192:195], v[112:115]
	v_mfma_f32_16x16x32_bf16 v[104:107], v[146:149], v[200:203], v[104:107]
	v_mfma_f32_16x16x32_bf16 v[96:99], v[158:161], v[200:203], v[96:99]
	v_mfma_f32_16x16x32_bf16 v[88:91], v[146:149], v[208:211], v[88:91]
	v_mfma_f32_16x16x32_bf16 v[80:83], v[158:161], v[208:211], v[80:83]
	v_mfma_f32_16x16x32_bf16 v[72:75], v[146:149], v[216:219], v[72:75]
	v_mfma_f32_16x16x32_bf16 v[64:67], v[158:161], v[216:219], v[64:67]
	v_mfma_f32_16x16x32_bf16 v[120:123], v[154:157], v[196:199], v[120:123]
	v_mfma_f32_16x16x32_bf16 v[112:115], v[162:165], v[196:199], v[112:115]
	v_mfma_f32_16x16x32_bf16 v[104:107], v[154:157], v[204:207], v[104:107]
	v_mfma_f32_16x16x32_bf16 v[96:99], v[162:165], v[204:207], v[96:99]
	v_mfma_f32_16x16x32_bf16 v[88:91], v[154:157], v[212:215], v[88:91]
	v_mfma_f32_16x16x32_bf16 v[80:83], v[162:165], v[212:215], v[80:83]
	v_mfma_f32_16x16x32_bf16 v[72:75], v[154:157], v[240:243], v[72:75]
	v_mfma_f32_16x16x32_bf16 v[64:67], v[162:165], v[240:243], v[64:67]
	v_mfma_f32_16x16x32_bf16 v[124:127], v[176:179], v[192:195], v[124:127]
	v_mfma_f32_16x16x32_bf16 v[116:119], v[184:187], v[192:195], v[116:119]
	v_mfma_f32_16x16x32_bf16 v[108:111], v[176:179], v[200:203], v[108:111]
	v_mfma_f32_16x16x32_bf16 v[100:103], v[184:187], v[200:203], v[100:103]
	v_mfma_f32_16x16x32_bf16 v[92:95], v[176:179], v[208:211], v[92:95]
	v_mfma_f32_16x16x32_bf16 v[84:87], v[184:187], v[208:211], v[84:87]
	v_mfma_f32_16x16x32_bf16 v[76:79], v[176:179], v[216:219], v[76:79]
	v_mfma_f32_16x16x32_bf16 v[68:71], v[184:187], v[216:219], v[68:71]
	v_mfma_f32_16x16x32_bf16 v[124:127], v[180:183], v[196:199], v[124:127]
	v_mfma_f32_16x16x32_bf16 v[116:119], v[188:191], v[196:199], v[116:119]
	v_mfma_f32_16x16x32_bf16 v[108:111], v[180:183], v[204:207], v[108:111]
	v_mfma_f32_16x16x32_bf16 v[100:103], v[188:191], v[204:207], v[100:103]
	v_mfma_f32_16x16x32_bf16 v[92:95], v[180:183], v[212:215], v[92:95]
	v_mfma_f32_16x16x32_bf16 v[84:87], v[188:191], v[212:215], v[84:87]
	v_mfma_f32_16x16x32_bf16 v[76:79], v[180:183], v[240:243], v[76:79]
	v_mfma_f32_16x16x32_bf16 v[68:71], v[188:191], v[240:243], v[68:71]
	s_setprio 0
	s_barrier
	s_add_i32 s65, s33, s45
	v_lshl_add_u64 v[226:227], v[220:221], 0, v[168:169]
	s_mov_b32 m0, s65
	ds_read_b128 v[192:195], v153 offset:16384
	ds_read_b128 v[196:199], v153 offset:17408
	ds_read_b128 v[200:203], v153 offset:18432
	ds_read_b128 v[204:207], v153 offset:19456
	ds_read_b128 v[208:211], v153 offset:20480
	ds_read_b128 v[212:215], v153 offset:21504
	ds_read_b128 v[216:219], v153 offset:22528
	ds_read_b128 v[240:243], v153 offset:23552
	global_load_lds_dwordx4 v[226:227], off
	v_lshl_add_u64 v[244:245], v[220:221], 0, v[128:129]
	s_add_i32 m0, s65, 0x2000
	v_lshl_add_u64 v[220:221], v[220:221], 0, s[12:13]
	s_add_i32 s10, s10, s45
	global_load_lds_dwordx4 v[244:245], off
	v_lshl_add_u64 v[246:247], v[220:221], 0, v[168:169]
	s_mov_b32 m0, s10
	v_lshl_add_u64 v[220:221], v[220:221], 0, v[128:129]
	global_load_lds_dwordx4 v[246:247], off
	s_add_i32 m0, s10, 0x2000
	v_lshl_add_u64 v[248:249], v[166:167], 0, v[132:133]
	global_load_lds_dwordx4 v[220:221], off
	s_mov_b32 m0, s51
	v_lshl_add_u64 v[250:251], v[166:167], 0, v[130:131]
	global_load_lds_dwordx4 v[248:249], off
	s_mov_b32 m0, s52
	s_nop 0
	global_load_lds_dwordx4 v[250:251], off
	s_waitcnt vmcnt(8)
	s_waitcnt lgkmcnt(0)
	s_barrier
; #define PG8_STAGE(bufoff, gbase, voff) do { _Pragma("unroll") for (int _i = 0; _i < 2; ++_i) \
;         __builtin_amdgcn_global_load_lds((const unsigned*)((const char*)(gbase) + (voff)[_i]), (LAS unsigned*)(lds + (bufoff) + ldsw + _i * 8192), 16, 0, 0); } while (0)
; #define PG8_LDA(dst, b, h) do { _Pragma("unroll") for (int m = 0; m < 4; ++m) _Pragma("unroll") for (int k = 0; k < 2; ++k) dst[m][k] = *(const LAS bf16x8*)(lds + PG8_SA(b, h) + aoff + m * 2048 + k * 1024); } while (0)
; #define PG8_LDB(dst, b, h) do { _Pragma("unroll") for (int n = 0; n < 2; ++n) _Pragma("unroll") for (int k = 0; k < 2; ++k) dst[n][k] = *(const LAS bf16x8*)(lds + PG8_SB(b, h) + boff + n * 2048 + k * 1024); } while (0)
; #define PG8_MMA(ai, bj, At, Bt) do { __builtin_amdgcn_s_setprio(1); _Pragma("unroll") for (int k = 0; k < 2; ++k) _Pragma("unroll") for (int m = 0; m < 4; ++m) _Pragma("unroll") for (int n = 0; n < 2; ++n) \
;         acc[ai][bj][m][n] = __builtin_amdgcn_mfma_f32_16x16x32_bf16(Bt[n][k], At[m][k], acc[ai][bj][m][n], 0, 0, 0); __builtin_amdgcn_s_setprio(0); } while (0)
; #define PG8_WAIT_V(n) asm volatile("s_waitcnt vmcnt(" #n ")" ::: "memory")
; #define PG8_WAIT_L(n) asm volatile("s_waitcnt lgkmcnt(" #n ")" ::: "memory")
; #define PG8_BAR __builtin_amdgcn_s_barrier()
; #define PG8_SCHED __builtin_amdgcn_sched_barrier(0)
; template <class Epi, bool ALIGN_EPI>
; __device__ __forceinline__ void gemm_phase(LAS unsigned char* lds, const Gemm g, const StaticOrder& S, const Epi& E, const int tid) {
;     ...
;             PG8_WAIT_V(8); PG8_WAIT_L(0); PG8_BAR; PG8_MMA(1, 0, At, B0); PG8_MMA(1, 1, At, B1); PG8_BAR; PG8_SCHED;
;             PG8_LDB(B0, 1, 0); PG8_LDB(B1, 1, 1); PG8_SCHED; PG8_LDA(At, 1, 0); PG8_STAGE(PG8_SA(0, 1), a2 + hA, voffA);
;             PG8_WAIT_V(8); PG8_WAIT_L(0); PG8_BAR; PG8_MMA(0, 0, At, B0); PG8_MMA(0, 1, At, B1); PG8_BAR; PG8_SCHED;
	s_setprio 1
	s_waitcnt lgkmcnt(0)
	v_mfma_f32_16x16x32_bf16 v[56:59], v[146:149], v[192:195], v[56:59]
	v_mfma_f32_16x16x32_bf16 v[48:51], v[158:161], v[192:195], v[48:51]
	v_mfma_f32_16x16x32_bf16 v[40:43], v[146:149], v[200:203], v[40:43]
	v_mfma_f32_16x16x32_bf16 v[32:35], v[158:161], v[200:203], v[32:35]
	v_mfma_f32_16x16x32_bf16 v[24:27], v[146:149], v[208:211], v[24:27]
	v_mfma_f32_16x16x32_bf16 v[16:19], v[158:161], v[208:211], v[16:19]
	v_mfma_f32_16x16x32_bf16 v[8:11], v[146:149], v[216:219], v[8:11]
	v_mfma_f32_16x16x32_bf16 v[4:7], v[158:161], v[216:219], v[4:7]
	v_mfma_f32_16x16x32_bf16 v[56:59], v[154:157], v[196:199], v[56:59]
	v_mfma_f32_16x16x32_bf16 v[48:51], v[162:165], v[196:199], v[48:51]
	v_mfma_f32_16x16x32_bf16 v[40:43], v[154:157], v[204:207], v[40:43]
	v_mfma_f32_16x16x32_bf16 v[32:35], v[162:165], v[204:207], v[32:35]
	v_mfma_f32_16x16x32_bf16 v[24:27], v[154:157], v[212:215], v[24:27]
	v_mfma_f32_16x16x32_bf16 v[16:19], v[162:165], v[212:215], v[16:19]
	v_mfma_f32_16x16x32_bf16 v[8:11], v[154:157], v[240:243], v[8:11]
	v_mfma_f32_16x16x32_bf16 v[4:7], v[162:165], v[240:243], v[4:7]
	v_mfma_f32_16x16x32_bf16 v[60:63], v[176:179], v[192:195], v[60:63]
	v_mfma_f32_16x16x32_bf16 v[52:55], v[184:187], v[192:195], v[52:55]
	v_mfma_f32_16x16x32_bf16 v[44:47], v[176:179], v[200:203], v[44:47]
	v_mfma_f32_16x16x32_bf16 v[36:39], v[184:187], v[200:203], v[36:39]
	v_mfma_f32_16x16x32_bf16 v[28:31], v[176:179], v[208:211], v[28:31]
	v_mfma_f32_16x16x32_bf16 v[20:23], v[184:187], v[208:211], v[20:23]
	v_mfma_f32_16x16x32_bf16 v[12:15], v[176:179], v[216:219], v[12:15]
	v_mfma_f32_16x16x32_bf16 v[0:3], v[184:187], v[216:219], v[0:3]
	v_mfma_f32_16x16x32_bf16 v[60:63], v[180:183], v[196:199], v[60:63]
	v_mfma_f32_16x16x32_bf16 v[52:55], v[188:191], v[196:199], v[52:55]
	v_mfma_f32_16x16x32_bf16 v[44:47], v[180:183], v[204:207], v[44:47]
	v_mfma_f32_16x16x32_bf16 v[36:39], v[188:191], v[204:207], v[36:39]
	v_mfma_f32_16x16x32_bf16 v[28:31], v[180:183], v[212:215], v[28:31]
	v_mfma_f32_16x16x32_bf16 v[20:23], v[188:191], v[212:215], v[20:23]
	v_mfma_f32_16x16x32_bf16 v[12:15], v[180:183], v[240:243], v[12:15]
	v_mfma_f32_16x16x32_bf16 v[0:3], v[188:191], v[240:243], v[0:3]
	s_setprio 0
	s_barrier
	s_add_i32 s10, 0, 0x18000
	v_add_u32_e32 v150, s10, v151
	s_add_i32 s65, 0, 0x1c000
	ds_read_b128 v[146:149], v150
	ds_read_b128 v[154:157], v150 offset:1024
	ds_read_b128 v[158:161], v150 offset:2048
	ds_read_b128 v[162:165], v150 offset:3072
	v_add_u32_e32 v150, s65, v151
	ds_read_b128 v[176:179], v150
	ds_read_b128 v[180:183], v150 offset:1024
	ds_read_b128 v[184:187], v150 offset:2048
	ds_read_b128 v[188:191], v150 offset:3072
	v_lshl_add_u64 v[166:167], v[166:167], 0, s[94:95]
	s_mov_b32 m0, s53
	v_lshl_add_u64 v[252:253], v[166:167], 0, v[132:133]
	ds_read_b128 v[192:195], v153 offset:32768
	ds_read_b128 v[196:199], v153 offset:33792
	ds_read_b128 v[200:203], v153 offset:34816
	ds_read_b128 v[204:207], v153 offset:35840
	ds_read_b128 v[208:211], v153 offset:36864
	ds_read_b128 v[212:215], v153 offset:37888
	ds_read_b128 v[216:219], v153 offset:38912
	ds_read_b128 v[240:243], v153 offset:39936
	global_load_lds_dwordx4 v[252:253], off
	v_lshl_add_u64 v[166:167], v[166:167], 0, v[130:131]
	s_mov_b32 m0, s54
	s_nop 0
	global_load_lds_dwordx4 v[166:167], off
	s_waitcnt vmcnt(8)
	s_waitcnt lgkmcnt(0)
	s_barrier
	s_setprio 1
	s_waitcnt lgkmcnt(0)
	v_mfma_f32_16x16x32_bf16 v[120:123], v[146:149], v[192:195], v[120:123]
	v_mfma_f32_16x16x32_bf16 v[112:115], v[158:161], v[192:195], v[112:115]
	v_mfma_f32_16x16x32_bf16 v[104:107], v[146:149], v[200:203], v[104:107]
	v_mfma_f32_16x16x32_bf16 v[96:99], v[158:161], v[200:203], v[96:99]
	v_mfma_f32_16x16x32_bf16 v[88:91], v[146:149], v[208:211], v[88:91]
	v_mfma_f32_16x16x32_bf16 v[80:83], v[158:161], v[208:211], v[80:83]
	v_mfma_f32_16x16x32_bf16 v[72:75], v[146:149], v[216:219], v[72:75]
	v_mfma_f32_16x16x32_bf16 v[64:67], v[158:161], v[216:219], v[64:67]
	v_mfma_f32_16x16x32_bf16 v[120:123], v[154:157], v[196:199], v[120:123]
	v_mfma_f32_16x16x32_bf16 v[112:115], v[162:165], v[196:199], v[112:115]
	v_mfma_f32_16x16x32_bf16 v[104:107], v[154:157], v[204:207], v[104:107]
	v_mfma_f32_16x16x32_bf16 v[96:99], v[162:165], v[204:207], v[96:99]
	v_mfma_f32_16x16x32_bf16 v[88:91], v[154:157], v[212:215], v[88:91]
	v_mfma_f32_16x16x32_bf16 v[80:83], v[162:165], v[212:215], v[80:83]
	v_mfma_f32_16x16x32_bf16 v[72:75], v[154:157], v[240:243], v[72:75]
	v_mfma_f32_16x16x32_bf16 v[64:67], v[162:165], v[240:243], v[64:67]
	v_mfma_f32_16x16x32_bf16 v[124:127], v[176:179], v[192:195], v[124:127]
	v_mfma_f32_16x16x32_bf16 v[116:119], v[184:187], v[192:195], v[116:119]
	v_mfma_f32_16x16x32_bf16 v[108:111], v[176:179], v[200:203], v[108:111]
	v_mfma_f32_16x16x32_bf16 v[100:103], v[184:187], v[200:203], v[100:103]
	v_mfma_f32_16x16x32_bf16 v[92:95], v[176:179], v[208:211], v[92:95]
	v_mfma_f32_16x16x32_bf16 v[84:87], v[184:187], v[208:211], v[84:87]
	v_mfma_f32_16x16x32_bf16 v[76:79], v[176:179], v[216:219], v[76:79]
	v_mfma_f32_16x16x32_bf16 v[68:71], v[184:187], v[216:219], v[68:71]
	v_mfma_f32_16x16x32_bf16 v[124:127], v[180:183], v[196:199], v[124:127]
	v_mfma_f32_16x16x32_bf16 v[116:119], v[188:191], v[196:199], v[116:119]
	v_mfma_f32_16x16x32_bf16 v[108:111], v[180:183], v[204:207], v[108:111]
	v_mfma_f32_16x16x32_bf16 v[100:103], v[188:191], v[204:207], v[100:103]
	v_mfma_f32_16x16x32_bf16 v[92:95], v[180:183], v[212:215], v[92:95]
	v_mfma_f32_16x16x32_bf16 v[84:87], v[188:191], v[212:215], v[84:87]
	v_mfma_f32_16x16x32_bf16 v[76:79], v[180:183], v[240:243], v[76:79]
	v_mfma_f32_16x16x32_bf16 v[68:71], v[188:191], v[240:243], v[68:71]
	s_setprio 0
	s_barrier
; #define PG8_STAGE(bufoff, gbase, voff) do { _Pragma("unroll") for (int _i = 0; _i < 2; ++_i) \
;         __builtin_amdgcn_global_load_lds((const unsigned*)((const char*)(gbase) + (voff)[_i]), (LAS unsigned*)(lds + (bufoff) + ldsw + _i * 8192), 16, 0, 0); } while (0)
; #define PG8_LDA(dst, b, h) do { _Pragma("unroll") for (int m = 0; m < 4; ++m) _Pragma("unroll") for (int k = 0; k < 2; ++k) dst[m][k] = *(const LAS bf16x8*)(lds + PG8_SA(b, h) + aoff + m * 2048 + k * 1024); } while (0)
; #define PG8_MMA(ai, bj, At, Bt) do { __builtin_amdgcn_s_setprio(1); _Pragma("unroll") for (int k = 0; k < 2; ++k) _Pragma("unroll") for (int m = 0; m < 4; ++m) _Pragma("unroll") for (int n = 0; n < 2; ++n) \
;         acc[ai][bj][m][n] = __builtin_amdgcn_mfma_f32_16x16x32_bf16(Bt[n][k], At[m][k], acc[ai][bj][m][n], 0, 0, 0); __builtin_amdgcn_s_setprio(0); } while (0)
; #define PG8_WAIT_V(n) asm volatile("s_waitcnt vmcnt(" #n ")" ::: "memory")
; #define PG8_WAIT_L(n) asm volatile("s_waitcnt lgkmcnt(" #n ")" ::: "memory")
; #define PG8_BAR __builtin_amdgcn_s_barrier()
; #define PG8_SCHED __builtin_amdgcn_sched_barrier(0)
; template <class Epi, bool ALIGN_EPI>
; __device__ __forceinline__ void gemm_phase(LAS unsigned char* lds, const Gemm g, const StaticOrder& S, const Epi& E, const int tid) {
;     ...
;             PG8_LDA(At, 1, 1); PG8_STAGE(PG8_SB(1, 0), b3, voffB); PG8_STAGE(PG8_SB(1, 1), b3 + hB, voffB); PG8_STAGE(PG8_SA(1, 0), a3, voffA);
;             PG8_WAIT_V(8); PG8_WAIT_L(0); PG8_BAR; PG8_MMA(1, 0, At, B0); PG8_MMA(1, 1, At, B1); PG8_BAR; PG8_SCHED;
;         }
	s_add_i32 s10, s10, s45
	v_lshl_add_u64 v[166:167], v[226:227], 0, s[92:93]
	s_mov_b32 m0, s10
	ds_read_b128 v[192:195], v153 offset:49152
	ds_read_b128 v[196:199], v153 offset:50176
	ds_read_b128 v[200:203], v153 offset:51200
	ds_read_b128 v[204:207], v153 offset:52224
	ds_read_b128 v[208:211], v153 offset:53248
	ds_read_b128 v[212:215], v153 offset:54272
	ds_read_b128 v[216:219], v153 offset:55296
	ds_read_b128 v[240:243], v153 offset:56320
	global_load_lds_dwordx4 v[166:167], off
	v_lshl_add_u64 v[166:167], v[244:245], 0, s[92:93]
	s_add_i32 m0, s10, 0x2000
	s_add_i32 s10, s65, s45
	global_load_lds_dwordx4 v[166:167], off
	v_lshl_add_u64 v[166:167], v[246:247], 0, s[92:93]
	s_mov_b32 m0, s10
	s_nop 0
	global_load_lds_dwordx4 v[166:167], off
	v_lshl_add_u64 v[166:167], v[220:221], 0, s[92:93]
	s_add_i32 m0, s10, 0x2000
	s_nop 0
	global_load_lds_dwordx4 v[166:167], off
	v_lshl_add_u64 v[166:167], v[248:249], 0, s[92:93]
	s_mov_b32 m0, s56
	s_nop 0
	global_load_lds_dwordx4 v[166:167], off
	v_lshl_add_u64 v[166:167], v[250:251], 0, s[92:93]
	s_mov_b32 m0, s57
	s_nop 0
	global_load_lds_dwordx4 v[166:167], off
	s_waitcnt vmcnt(8)
	s_waitcnt lgkmcnt(0)
	s_barrier
	s_setprio 1
	s_waitcnt lgkmcnt(0)
	v_mfma_f32_16x16x32_bf16 v[56:59], v[146:149], v[192:195], v[56:59]
	v_mfma_f32_16x16x32_bf16 v[48:51], v[158:161], v[192:195], v[48:51]
	v_mfma_f32_16x16x32_bf16 v[40:43], v[146:149], v[200:203], v[40:43]
	v_mfma_f32_16x16x32_bf16 v[32:35], v[158:161], v[200:203], v[32:35]
	v_mfma_f32_16x16x32_bf16 v[24:27], v[146:149], v[208:211], v[24:27]
	v_mfma_f32_16x16x32_bf16 v[16:19], v[158:161], v[208:211], v[16:19]
	v_mfma_f32_16x16x32_bf16 v[8:11], v[146:149], v[216:219], v[8:11]
	v_mfma_f32_16x16x32_bf16 v[4:7], v[158:161], v[216:219], v[4:7]
	v_mfma_f32_16x16x32_bf16 v[56:59], v[154:157], v[196:199], v[56:59]
	v_mfma_f32_16x16x32_bf16 v[48:51], v[162:165], v[196:199], v[48:51]
	v_mfma_f32_16x16x32_bf16 v[40:43], v[154:157], v[204:207], v[40:43]
	v_mfma_f32_16x16x32_bf16 v[32:35], v[162:165], v[204:207], v[32:35]
	v_mfma_f32_16x16x32_bf16 v[24:27], v[154:157], v[212:215], v[24:27]
	v_mfma_f32_16x16x32_bf16 v[16:19], v[162:165], v[212:215], v[16:19]
	v_mfma_f32_16x16x32_bf16 v[8:11], v[154:157], v[240:243], v[8:11]
	v_mfma_f32_16x16x32_bf16 v[4:7], v[162:165], v[240:243], v[4:7]
	v_mfma_f32_16x16x32_bf16 v[60:63], v[176:179], v[192:195], v[60:63]
	v_mfma_f32_16x16x32_bf16 v[52:55], v[184:187], v[192:195], v[52:55]
	v_mfma_f32_16x16x32_bf16 v[44:47], v[176:179], v[200:203], v[44:47]
	v_mfma_f32_16x16x32_bf16 v[36:39], v[184:187], v[200:203], v[36:39]
	v_mfma_f32_16x16x32_bf16 v[28:31], v[176:179], v[208:211], v[28:31]
	v_mfma_f32_16x16x32_bf16 v[20:23], v[184:187], v[208:211], v[20:23]
	v_mfma_f32_16x16x32_bf16 v[12:15], v[176:179], v[216:219], v[12:15]
	v_mfma_f32_16x16x32_bf16 v[0:3], v[184:187], v[216:219], v[0:3]
	v_mfma_f32_16x16x32_bf16 v[60:63], v[180:183], v[196:199], v[60:63]
	v_mfma_f32_16x16x32_bf16 v[52:55], v[188:191], v[196:199], v[52:55]
	v_mfma_f32_16x16x32_bf16 v[44:47], v[180:183], v[204:207], v[44:47]
	v_mfma_f32_16x16x32_bf16 v[36:39], v[188:191], v[204:207], v[36:39]
	v_mfma_f32_16x16x32_bf16 v[28:31], v[180:183], v[212:215], v[28:31]
	v_mfma_f32_16x16x32_bf16 v[20:23], v[188:191], v[212:215], v[20:23]
	v_mfma_f32_16x16x32_bf16 v[12:15], v[180:183], v[240:243], v[12:15]
	v_mfma_f32_16x16x32_bf16 v[0:3], v[188:191], v[240:243], v[0:3]
	s_setprio 0
	s_barrier
	v_lshl_add_u64 v[142:143], v[142:143], 0, s[80:81]
	v_lshl_add_u64 v[144:145], v[144:145], 0, s[80:81]
	s_cmp_ge_u32 s11, s55
	s_mov_b32 s10, s11
	s_cbranch_scc0 .LBB0_308

; #define PG8_STAGE(bufoff, gbase, voff) do { _Pragma("unroll") for (int _i = 0; _i < 2; ++_i) \
;         __builtin_amdgcn_global_load_lds((const unsigned*)((const char*)(gbase) + (voff)[_i]), (LAS unsigned*)(lds + (bufoff) + ldsw + _i * 8192), 16, 0, 0); } while (0)
; #define PG8_LDA(dst, b, h) do { _Pragma("unroll") for (int m = 0; m < 4; ++m) _Pragma("unroll") for (int k = 0; k < 2; ++k) dst[m][k] = *(const LAS bf16x8*)(lds + PG8_SA(b, h) + aoff + m * 2048 + k * 1024); } while (0)
; #define PG8_LDB(dst, b, h) do { _Pragma("unroll") for (int n = 0; n < 2; ++n) _Pragma("unroll") for (int k = 0; k < 2; ++k) dst[n][k] = *(const LAS bf16x8*)(lds + PG8_SB(b, h) + boff + n * 2048 + k * 1024); } while (0)
; #define PG8_MMA(ai, bj, At, Bt) do { __builtin_amdgcn_s_setprio(1); _Pragma("unroll") for (int k = 0; k < 2; ++k) _Pragma("unroll") for (int m = 0; m < 4; ++m) _Pragma("unroll") for (int n = 0; n < 2; ++n) \
;         acc[ai][bj][m][n] = __builtin_amdgcn_mfma_f32_16x16x32_bf16(Bt[n][k], At[m][k], acc[ai][bj][m][n], 0, 0, 0); __builtin_amdgcn_s_setprio(0); } while (0)
; #define PG8_WAIT_V(n) asm volatile("s_waitcnt vmcnt(" #n ")" ::: "memory")
; #define PG8_WAIT_L(n) asm volatile("s_waitcnt lgkmcnt(" #n ")" ::: "memory")
; #define PG8_BAR __builtin_amdgcn_s_barrier()
; #define PG8_SCHED __builtin_amdgcn_sched_barrier(0)
; template <class Epi, bool ALIGN_EPI>
; __device__ __forceinline__ void gemm_phase(LAS unsigned char* lds, const Gemm g, const StaticOrder& S, const Epi& E, const int tid) {
;     ...
;             const bool last = (t == nt - 2);
;             const char* a1 = cA + (size_t)(t + 1) * kstep;
;             const char* a2 = last ? nA : cA + (size_t)(t + 2) * kstep; const char* b2 = last ? nB : cB + (size_t)(t + 2) * kstep;
;             const char* a3 = a2 + kstep; const char* b3 = b2 + kstep;
;             PG8_LDB(B0, 0, 0); PG8_LDB(B1, 0, 1); PG8_SCHED; PG8_LDA(At, 0, 0); PG8_STAGE(PG8_SA(1, 1), a1 + hA, voffA);
;             PG8_WAIT_V(8); PG8_WAIT_L(0); PG8_BAR; PG8_MMA(0, 0, At, B0); PG8_MMA(0, 1, At, B1); PG8_BAR; PG8_SCHED;
;             PG8_LDA(At, 0, 1); PG8_STAGE(PG8_SB(0, 0), b2, voffB); PG8_STAGE(PG8_SB(0, 1), b2 + hB, voffB); PG8_STAGE(PG8_SA(0, 0), a2, voffA);
;             PG8_WAIT_V(8); PG8_WAIT_L(0); PG8_BAR; PG8_MMA(1, 0, At, B0); PG8_MMA(1, 1, At, B1); PG8_BAR; PG8_SCHED;
.LBB0_331:
	s_add_i32 s11, s10, 2
	s_cmp_eq_u32 s58, s10
	v_lshl_add_u64 v[146:147], v[142:143], 0, s[92:93]
	s_cselect_b64 vcc, -1, 0
	v_add_u32_e32 v152, s33, v153
	s_add_i32 s10, 0, 0x14000
	v_cndmask_b32_e32 v151, v147, v139, vcc
	v_cndmask_b32_e32 v150, v146, v138, vcc
	ds_read_b128 v[146:149], v152
	ds_read_b128 v[156:159], v152 offset:1024
	ds_read_b128 v[160:163], v152 offset:2048
	ds_read_b128 v[164:167], v152 offset:3072
	v_add_u32_e32 v152, s10, v153
	ds_read_b128 v[176:179], v152
	ds_read_b128 v[180:183], v152 offset:1024
	ds_read_b128 v[184:187], v152 offset:2048
	ds_read_b128 v[188:191], v152 offset:3072
	v_cndmask_b32_e32 v221, v145, v141, vcc
	v_cndmask_b32_e32 v220, v144, v140, vcc
	v_lshl_add_u64 v[226:227], v[142:143], 0, v[134:135]
	s_add_i32 m0, s51, 0xc000
	ds_read_b128 v[192:195], v155
	ds_read_b128 v[196:199], v155 offset:1024
	ds_read_b128 v[200:203], v155 offset:2048
	ds_read_b128 v[204:207], v155 offset:3072
	ds_read_b128 v[208:211], v155 offset:4096
	ds_read_b128 v[212:215], v155 offset:5120
	ds_read_b128 v[216:219], v155 offset:6144
	ds_read_b128 v[240:243], v155 offset:7168
	global_load_lds_dwordx4 v[226:227], off
	v_lshl_add_u64 v[226:227], v[142:143], 0, v[136:137]
	s_add_i32 m0, s51, 0xe000
	s_nop 0
	global_load_lds_dwordx4 v[226:227], off
	s_waitcnt vmcnt(8)
	s_waitcnt lgkmcnt(0)
	s_barrier
	s_setprio 1
	s_waitcnt lgkmcnt(0)
	v_mfma_f32_16x16x32_bf16 v[120:123], v[146:149], v[192:195], v[120:123]
	v_mfma_f32_16x16x32_bf16 v[124:127], v[160:163], v[192:195], v[124:127]
	v_mfma_f32_16x16x32_bf16 v[108:111], v[146:149], v[200:203], v[108:111]
	v_mfma_f32_16x16x32_bf16 v[104:107], v[160:163], v[200:203], v[104:107]
	v_mfma_f32_16x16x32_bf16 v[92:95], v[146:149], v[208:211], v[92:95]
	v_mfma_f32_16x16x32_bf16 v[88:91], v[160:163], v[208:211], v[88:91]
	v_mfma_f32_16x16x32_bf16 v[76:79], v[146:149], v[216:219], v[76:79]
	v_mfma_f32_16x16x32_bf16 v[72:75], v[160:163], v[216:219], v[72:75]
	v_mfma_f32_16x16x32_bf16 v[120:123], v[156:159], v[196:199], v[120:123]
	v_mfma_f32_16x16x32_bf16 v[124:127], v[164:167], v[196:199], v[124:127]
	v_mfma_f32_16x16x32_bf16 v[108:111], v[156:159], v[204:207], v[108:111]
	v_mfma_f32_16x16x32_bf16 v[104:107], v[164:167], v[204:207], v[104:107]
	v_mfma_f32_16x16x32_bf16 v[92:95], v[156:159], v[212:215], v[92:95]
	v_mfma_f32_16x16x32_bf16 v[88:91], v[164:167], v[212:215], v[88:91]
	v_mfma_f32_16x16x32_bf16 v[76:79], v[156:159], v[240:243], v[76:79]
	v_mfma_f32_16x16x32_bf16 v[72:75], v[164:167], v[240:243], v[72:75]
	v_mfma_f32_16x16x32_bf16 v[116:119], v[176:179], v[192:195], v[116:119]
	v_mfma_f32_16x16x32_bf16 v[112:115], v[184:187], v[192:195], v[112:115]
	v_mfma_f32_16x16x32_bf16 v[100:103], v[176:179], v[200:203], v[100:103]
	v_mfma_f32_16x16x32_bf16 v[96:99], v[184:187], v[200:203], v[96:99]
	v_mfma_f32_16x16x32_bf16 v[84:87], v[176:179], v[208:211], v[84:87]
	v_mfma_f32_16x16x32_bf16 v[80:83], v[184:187], v[208:211], v[80:83]
	v_mfma_f32_16x16x32_bf16 v[68:71], v[176:179], v[216:219], v[68:71]
	v_mfma_f32_16x16x32_bf16 v[64:67], v[184:187], v[216:219], v[64:67]
	v_mfma_f32_16x16x32_bf16 v[116:119], v[180:183], v[196:199], v[116:119]
	v_mfma_f32_16x16x32_bf16 v[112:115], v[188:191], v[196:199], v[112:115]
	v_mfma_f32_16x16x32_bf16 v[100:103], v[180:183], v[204:207], v[100:103]
	v_mfma_f32_16x16x32_bf16 v[96:99], v[188:191], v[204:207], v[96:99]
	v_mfma_f32_16x16x32_bf16 v[84:87], v[180:183], v[212:215], v[84:87]
	v_mfma_f32_16x16x32_bf16 v[80:83], v[188:191], v[212:215], v[80:83]
	v_mfma_f32_16x16x32_bf16 v[68:71], v[180:183], v[240:243], v[68:71]
	v_mfma_f32_16x16x32_bf16 v[64:67], v[188:191], v[240:243], v[64:67]
	s_setprio 0
	s_barrier
	s_add_i32 s65, s33, s45
	v_lshl_add_u64 v[226:227], v[220:221], 0, v[168:169]
	s_mov_b32 m0, s65
	ds_read_b128 v[192:195], v155 offset:16384
	ds_read_b128 v[196:199], v155 offset:17408
	ds_read_b128 v[200:203], v155 offset:18432
	ds_read_b128 v[204:207], v155 offset:19456
	ds_read_b128 v[208:211], v155 offset:20480
	ds_read_b128 v[212:215], v155 offset:21504
	ds_read_b128 v[216:219], v155 offset:22528
	ds_read_b128 v[240:243], v155 offset:23552
	global_load_lds_dwordx4 v[226:227], off
	v_lshl_add_u64 v[244:245], v[220:221], 0, v[128:129]
	s_add_i32 m0, s65, 0x2000
	v_lshl_add_u64 v[220:221], v[220:221], 0, s[12:13]
	s_add_i32 s10, s10, s45
	global_load_lds_dwordx4 v[244:245], off
	v_lshl_add_u64 v[246:247], v[220:221], 0, v[168:169]
	s_mov_b32 m0, s10
	v_lshl_add_u64 v[220:221], v[220:221], 0, v[128:129]
	global_load_lds_dwordx4 v[246:247], off
	s_add_i32 m0, s10, 0x2000
	v_lshl_add_u64 v[248:249], v[150:151], 0, v[132:133]
	global_load_lds_dwordx4 v[220:221], off
	s_mov_b32 m0, s51
	v_lshl_add_u64 v[250:251], v[150:151], 0, v[130:131]
	global_load_lds_dwordx4 v[248:249], off
	s_mov_b32 m0, s52
	s_nop 0
	global_load_lds_dwordx4 v[250:251], off
	s_waitcnt vmcnt(8)
	s_waitcnt lgkmcnt(0)
	s_barrier
; #define PG8_STAGE(bufoff, gbase, voff) do { _Pragma("unroll") for (int _i = 0; _i < 2; ++_i) \
;         __builtin_amdgcn_global_load_lds((const unsigned*)((const char*)(gbase) + (voff)[_i]), (LAS unsigned*)(lds + (bufoff) + ldsw + _i * 8192), 16, 0, 0); } while (0)
; #define PG8_LDA(dst, b, h) do { _Pragma("unroll") for (int m = 0; m < 4; ++m) _Pragma("unroll") for (int k = 0; k < 2; ++k) dst[m][k] = *(const LAS bf16x8*)(lds + PG8_SA(b, h) + aoff + m * 2048 + k * 1024); } while (0)
; #define PG8_LDB(dst, b, h) do { _Pragma("unroll") for (int n = 0; n < 2; ++n) _Pragma("unroll") for (int k = 0; k < 2; ++k) dst[n][k] = *(const LAS bf16x8*)(lds + PG8_SB(b, h) + boff + n * 2048 + k * 1024); } while (0)
; #define PG8_MMA(ai, bj, At, Bt) do { __builtin_amdgcn_s_setprio(1); _Pragma("unroll") for (int k = 0; k < 2; ++k) _Pragma("unroll") for (int m = 0; m < 4; ++m) _Pragma("unroll") for (int n = 0; n < 2; ++n) \
;         acc[ai][bj][m][n] = __builtin_amdgcn_mfma_f32_16x16x32_bf16(Bt[n][k], At[m][k], acc[ai][bj][m][n], 0, 0, 0); __builtin_amdgcn_s_setprio(0); } while (0)
; #define PG8_WAIT_V(n) asm volatile("s_waitcnt vmcnt(" #n ")" ::: "memory")
; #define PG8_WAIT_L(n) asm volatile("s_waitcnt lgkmcnt(" #n ")" ::: "memory")
; #define PG8_BAR __builtin_amdgcn_s_barrier()
; #define PG8_SCHED __builtin_amdgcn_sched_barrier(0)
; template <class Epi, bool ALIGN_EPI>
; __device__ __forceinline__ void gemm_phase(LAS unsigned char* lds, const Gemm g, const StaticOrder& S, const Epi& E, const int tid) {
;     ...
;             PG8_WAIT_V(8); PG8_WAIT_L(0); PG8_BAR; PG8_MMA(1, 0, At, B0); PG8_MMA(1, 1, At, B1); PG8_BAR; PG8_SCHED;
;             PG8_LDB(B0, 1, 0); PG8_LDB(B1, 1, 1); PG8_SCHED; PG8_LDA(At, 1, 0); PG8_STAGE(PG8_SA(0, 1), a2 + hA, voffA);
;             PG8_WAIT_V(8); PG8_WAIT_L(0); PG8_BAR; PG8_MMA(0, 0, At, B0); PG8_MMA(0, 1, At, B1); PG8_BAR; PG8_SCHED;
	s_setprio 1
	s_waitcnt lgkmcnt(0)
	v_mfma_f32_16x16x32_bf16 v[60:63], v[146:149], v[192:195], v[60:63]
	v_mfma_f32_16x16x32_bf16 v[56:59], v[160:163], v[192:195], v[56:59]
	v_mfma_f32_16x16x32_bf16 v[44:47], v[146:149], v[200:203], v[44:47]
	v_mfma_f32_16x16x32_bf16 v[40:43], v[160:163], v[200:203], v[40:43]
	v_mfma_f32_16x16x32_bf16 v[28:31], v[146:149], v[208:211], v[28:31]
	v_mfma_f32_16x16x32_bf16 v[24:27], v[160:163], v[208:211], v[24:27]
	v_mfma_f32_16x16x32_bf16 v[12:15], v[146:149], v[216:219], v[12:15]
	v_mfma_f32_16x16x32_bf16 v[8:11], v[160:163], v[216:219], v[8:11]
	v_mfma_f32_16x16x32_bf16 v[60:63], v[156:159], v[196:199], v[60:63]
	v_mfma_f32_16x16x32_bf16 v[56:59], v[164:167], v[196:199], v[56:59]
	v_mfma_f32_16x16x32_bf16 v[44:47], v[156:159], v[204:207], v[44:47]
	v_mfma_f32_16x16x32_bf16 v[40:43], v[164:167], v[204:207], v[40:43]
	v_mfma_f32_16x16x32_bf16 v[28:31], v[156:159], v[212:215], v[28:31]
	v_mfma_f32_16x16x32_bf16 v[24:27], v[164:167], v[212:215], v[24:27]
	v_mfma_f32_16x16x32_bf16 v[12:15], v[156:159], v[240:243], v[12:15]
	v_mfma_f32_16x16x32_bf16 v[8:11], v[164:167], v[240:243], v[8:11]
	v_mfma_f32_16x16x32_bf16 v[52:55], v[176:179], v[192:195], v[52:55]
	v_mfma_f32_16x16x32_bf16 v[48:51], v[184:187], v[192:195], v[48:51]
	v_mfma_f32_16x16x32_bf16 v[36:39], v[176:179], v[200:203], v[36:39]
	v_mfma_f32_16x16x32_bf16 v[32:35], v[184:187], v[200:203], v[32:35]
	v_mfma_f32_16x16x32_bf16 v[20:23], v[176:179], v[208:211], v[20:23]
	v_mfma_f32_16x16x32_bf16 v[16:19], v[184:187], v[208:211], v[16:19]
	v_mfma_f32_16x16x32_bf16 v[4:7], v[176:179], v[216:219], v[4:7]
	v_mfma_f32_16x16x32_bf16 v[0:3], v[184:187], v[216:219], v[0:3]
	v_mfma_f32_16x16x32_bf16 v[52:55], v[180:183], v[196:199], v[52:55]
	v_mfma_f32_16x16x32_bf16 v[48:51], v[188:191], v[196:199], v[48:51]
	v_mfma_f32_16x16x32_bf16 v[36:39], v[180:183], v[204:207], v[36:39]
	v_mfma_f32_16x16x32_bf16 v[32:35], v[188:191], v[204:207], v[32:35]
	v_mfma_f32_16x16x32_bf16 v[20:23], v[180:183], v[212:215], v[20:23]
	v_mfma_f32_16x16x32_bf16 v[16:19], v[188:191], v[212:215], v[16:19]
	v_mfma_f32_16x16x32_bf16 v[4:7], v[180:183], v[240:243], v[4:7]
	v_mfma_f32_16x16x32_bf16 v[0:3], v[188:191], v[240:243], v[0:3]
	s_setprio 0
	s_barrier
	s_add_i32 s10, 0, 0x18000
	v_add_u32_e32 v152, s10, v153
	s_add_i32 s65, 0, 0x1c000
	ds_read_b128 v[146:149], v152
	ds_read_b128 v[156:159], v152 offset:1024
	ds_read_b128 v[160:163], v152 offset:2048
	ds_read_b128 v[164:167], v152 offset:3072
	v_add_u32_e32 v152, s65, v153
	ds_read_b128 v[176:179], v152
	ds_read_b128 v[180:183], v152 offset:1024
	ds_read_b128 v[184:187], v152 offset:2048
	ds_read_b128 v[188:191], v152 offset:3072
	v_lshl_add_u64 v[150:151], v[150:151], 0, s[94:95]
	s_mov_b32 m0, s53
	v_lshl_add_u64 v[252:253], v[150:151], 0, v[132:133]
	ds_read_b128 v[192:195], v155 offset:32768
	ds_read_b128 v[196:199], v155 offset:33792
	ds_read_b128 v[200:203], v155 offset:34816
	ds_read_b128 v[204:207], v155 offset:35840
	ds_read_b128 v[208:211], v155 offset:36864
	ds_read_b128 v[212:215], v155 offset:37888
	ds_read_b128 v[216:219], v155 offset:38912
	ds_read_b128 v[240:243], v155 offset:39936
	global_load_lds_dwordx4 v[252:253], off
	v_lshl_add_u64 v[150:151], v[150:151], 0, v[130:131]
	s_mov_b32 m0, s54
	s_nop 0
	global_load_lds_dwordx4 v[150:151], off
	s_waitcnt vmcnt(8)
	s_waitcnt lgkmcnt(0)
	s_barrier
	s_setprio 1
	s_waitcnt lgkmcnt(0)
	v_mfma_f32_16x16x32_bf16 v[120:123], v[146:149], v[192:195], v[120:123]
	v_mfma_f32_16x16x32_bf16 v[124:127], v[160:163], v[192:195], v[124:127]
	v_mfma_f32_16x16x32_bf16 v[108:111], v[146:149], v[200:203], v[108:111]
	v_mfma_f32_16x16x32_bf16 v[104:107], v[160:163], v[200:203], v[104:107]
	v_mfma_f32_16x16x32_bf16 v[92:95], v[146:149], v[208:211], v[92:95]
	v_mfma_f32_16x16x32_bf16 v[88:91], v[160:163], v[208:211], v[88:91]
	v_mfma_f32_16x16x32_bf16 v[76:79], v[146:149], v[216:219], v[76:79]
	v_mfma_f32_16x16x32_bf16 v[72:75], v[160:163], v[216:219], v[72:75]
	v_mfma_f32_16x16x32_bf16 v[120:123], v[156:159], v[196:199], v[120:123]
	v_mfma_f32_16x16x32_bf16 v[124:127], v[164:167], v[196:199], v[124:127]
	v_mfma_f32_16x16x32_bf16 v[108:111], v[156:159], v[204:207], v[108:111]
	v_mfma_f32_16x16x32_bf16 v[104:107], v[164:167], v[204:207], v[104:107]
	v_mfma_f32_16x16x32_bf16 v[92:95], v[156:159], v[212:215], v[92:95]
	v_mfma_f32_16x16x32_bf16 v[88:91], v[164:167], v[212:215], v[88:91]
	v_mfma_f32_16x16x32_bf16 v[76:79], v[156:159], v[240:243], v[76:79]
	v_mfma_f32_16x16x32_bf16 v[72:75], v[164:167], v[240:243], v[72:75]
	v_mfma_f32_16x16x32_bf16 v[116:119], v[176:179], v[192:195], v[116:119]
	v_mfma_f32_16x16x32_bf16 v[112:115], v[184:187], v[192:195], v[112:115]
	v_mfma_f32_16x16x32_bf16 v[100:103], v[176:179], v[200:203], v[100:103]
	v_mfma_f32_16x16x32_bf16 v[96:99], v[184:187], v[200:203], v[96:99]
	v_mfma_f32_16x16x32_bf16 v[84:87], v[176:179], v[208:211], v[84:87]
	v_mfma_f32_16x16x32_bf16 v[80:83], v[184:187], v[208:211], v[80:83]
	v_mfma_f32_16x16x32_bf16 v[68:71], v[176:179], v[216:219], v[68:71]
	v_mfma_f32_16x16x32_bf16 v[64:67], v[184:187], v[216:219], v[64:67]
	v_mfma_f32_16x16x32_bf16 v[116:119], v[180:183], v[196:199], v[116:119]
	v_mfma_f32_16x16x32_bf16 v[112:115], v[188:191], v[196:199], v[112:115]
	v_mfma_f32_16x16x32_bf16 v[100:103], v[180:183], v[204:207], v[100:103]
	v_mfma_f32_16x16x32_bf16 v[96:99], v[188:191], v[204:207], v[96:99]
	v_mfma_f32_16x16x32_bf16 v[84:87], v[180:183], v[212:215], v[84:87]
	v_mfma_f32_16x16x32_bf16 v[80:83], v[188:191], v[212:215], v[80:83]
	v_mfma_f32_16x16x32_bf16 v[68:71], v[180:183], v[240:243], v[68:71]
	v_mfma_f32_16x16x32_bf16 v[64:67], v[188:191], v[240:243], v[64:67]
	s_setprio 0
	s_barrier
; #define PG8_STAGE(bufoff, gbase, voff) do { _Pragma("unroll") for (int _i = 0; _i < 2; ++_i) \
;         __builtin_amdgcn_global_load_lds((const unsigned*)((const char*)(gbase) + (voff)[_i]), (LAS unsigned*)(lds + (bufoff) + ldsw + _i * 8192), 16, 0, 0); } while (0)
; #define PG8_LDA(dst, b, h) do { _Pragma("unroll") for (int m = 0; m < 4; ++m) _Pragma("unroll") for (int k = 0; k < 2; ++k) dst[m][k] = *(const LAS bf16x8*)(lds + PG8_SA(b, h) + aoff + m * 2048 + k * 1024); } while (0)
; #define PG8_MMA(ai, bj, At, Bt) do { __builtin_amdgcn_s_setprio(1); _Pragma("unroll") for (int k = 0; k < 2; ++k) _Pragma("unroll") for (int m = 0; m < 4; ++m) _Pragma("unroll") for (int n = 0; n < 2; ++n) \
;         acc[ai][bj][m][n] = __builtin_amdgcn_mfma_f32_16x16x32_bf16(Bt[n][k], At[m][k], acc[ai][bj][m][n], 0, 0, 0); __builtin_amdgcn_s_setprio(0); } while (0)
; #define PG8_WAIT_V(n) asm volatile("s_waitcnt vmcnt(" #n ")" ::: "memory")
; #define PG8_WAIT_L(n) asm volatile("s_waitcnt lgkmcnt(" #n ")" ::: "memory")
; #define PG8_BAR __builtin_amdgcn_s_barrier()
; #define PG8_SCHED __builtin_amdgcn_sched_barrier(0)
; template <class Epi, bool ALIGN_EPI>
; __device__ __forceinline__ void gemm_phase(LAS unsigned char* lds, const Gemm g, const StaticOrder& S, const Epi& E, const int tid) {
;     ...
;             PG8_LDA(At, 1, 1); PG8_STAGE(PG8_SB(1, 0), b3, voffB); PG8_STAGE(PG8_SB(1, 1), b3 + hB, voffB); PG8_STAGE(PG8_SA(1, 0), a3, voffA);
;             PG8_WAIT_V(8); PG8_WAIT_L(0); PG8_BAR; PG8_MMA(1, 0, At, B0); PG8_MMA(1, 1, At, B1); PG8_BAR; PG8_SCHED;
;         }
	s_add_i32 s10, s10, s45
	v_lshl_add_u64 v[150:151], v[226:227], 0, s[92:93]
	s_mov_b32 m0, s10
	ds_read_b128 v[192:195], v155 offset:49152
	ds_read_b128 v[196:199], v155 offset:50176
	ds_read_b128 v[200:203], v155 offset:51200
	ds_read_b128 v[204:207], v155 offset:52224
	ds_read_b128 v[208:211], v155 offset:53248
	ds_read_b128 v[212:215], v155 offset:54272
	ds_read_b128 v[216:219], v155 offset:55296
	ds_read_b128 v[240:243], v155 offset:56320
	global_load_lds_dwordx4 v[150:151], off
	v_lshl_add_u64 v[150:151], v[244:245], 0, s[92:93]
	s_add_i32 m0, s10, 0x2000
	s_add_i32 s10, s65, s45
	global_load_lds_dwordx4 v[150:151], off
	v_lshl_add_u64 v[150:151], v[246:247], 0, s[92:93]
	s_mov_b32 m0, s10
	s_nop 0
	global_load_lds_dwordx4 v[150:151], off
	v_lshl_add_u64 v[150:151], v[220:221], 0, s[92:93]
	s_add_i32 m0, s10, 0x2000
	s_nop 0
	global_load_lds_dwordx4 v[150:151], off
	v_lshl_add_u64 v[150:151], v[248:249], 0, s[92:93]
	s_mov_b32 m0, s56
	s_nop 0
	global_load_lds_dwordx4 v[150:151], off
	v_lshl_add_u64 v[150:151], v[250:251], 0, s[92:93]
	s_mov_b32 m0, s57
	s_nop 0
	global_load_lds_dwordx4 v[150:151], off
	s_waitcnt vmcnt(8)
	s_waitcnt lgkmcnt(0)
	s_barrier
	s_setprio 1
	s_waitcnt lgkmcnt(0)
	v_mfma_f32_16x16x32_bf16 v[60:63], v[146:149], v[192:195], v[60:63]
	v_mfma_f32_16x16x32_bf16 v[56:59], v[160:163], v[192:195], v[56:59]
	v_mfma_f32_16x16x32_bf16 v[44:47], v[146:149], v[200:203], v[44:47]
	v_mfma_f32_16x16x32_bf16 v[40:43], v[160:163], v[200:203], v[40:43]
	v_mfma_f32_16x16x32_bf16 v[28:31], v[146:149], v[208:211], v[28:31]
	v_mfma_f32_16x16x32_bf16 v[24:27], v[160:163], v[208:211], v[24:27]
	v_mfma_f32_16x16x32_bf16 v[12:15], v[146:149], v[216:219], v[12:15]
	v_mfma_f32_16x16x32_bf16 v[8:11], v[160:163], v[216:219], v[8:11]
	v_mfma_f32_16x16x32_bf16 v[60:63], v[156:159], v[196:199], v[60:63]
	v_mfma_f32_16x16x32_bf16 v[56:59], v[164:167], v[196:199], v[56:59]
	v_mfma_f32_16x16x32_bf16 v[44:47], v[156:159], v[204:207], v[44:47]
	v_mfma_f32_16x16x32_bf16 v[40:43], v[164:167], v[204:207], v[40:43]
	v_mfma_f32_16x16x32_bf16 v[28:31], v[156:159], v[212:215], v[28:31]
	v_mfma_f32_16x16x32_bf16 v[24:27], v[164:167], v[212:215], v[24:27]
	v_mfma_f32_16x16x32_bf16 v[12:15], v[156:159], v[240:243], v[12:15]
	v_mfma_f32_16x16x32_bf16 v[8:11], v[164:167], v[240:243], v[8:11]
	v_mfma_f32_16x16x32_bf16 v[52:55], v[176:179], v[192:195], v[52:55]
	v_mfma_f32_16x16x32_bf16 v[48:51], v[184:187], v[192:195], v[48:51]
	v_mfma_f32_16x16x32_bf16 v[36:39], v[176:179], v[200:203], v[36:39]
	v_mfma_f32_16x16x32_bf16 v[32:35], v[184:187], v[200:203], v[32:35]
	v_mfma_f32_16x16x32_bf16 v[20:23], v[176:179], v[208:211], v[20:23]
	v_mfma_f32_16x16x32_bf16 v[16:19], v[184:187], v[208:211], v[16:19]
	v_mfma_f32_16x16x32_bf16 v[4:7], v[176:179], v[216:219], v[4:7]
	v_mfma_f32_16x16x32_bf16 v[0:3], v[184:187], v[216:219], v[0:3]
	v_mfma_f32_16x16x32_bf16 v[52:55], v[180:183], v[196:199], v[52:55]
	v_mfma_f32_16x16x32_bf16 v[48:51], v[188:191], v[196:199], v[48:51]
	v_mfma_f32_16x16x32_bf16 v[36:39], v[180:183], v[204:207], v[36:39]
	v_mfma_f32_16x16x32_bf16 v[32:35], v[188:191], v[204:207], v[32:35]
	v_mfma_f32_16x16x32_bf16 v[20:23], v[180:183], v[212:215], v[20:23]
	v_mfma_f32_16x16x32_bf16 v[16:19], v[188:191], v[212:215], v[16:19]
	v_mfma_f32_16x16x32_bf16 v[4:7], v[180:183], v[240:243], v[4:7]
	v_mfma_f32_16x16x32_bf16 v[0:3], v[188:191], v[240:243], v[0:3]
	s_setprio 0
	s_barrier
	v_lshl_add_u64 v[142:143], v[142:143], 0, s[80:81]
	v_lshl_add_u64 v[144:145], v[144:145], 0, s[80:81]
	s_cmp_ge_u32 s11, s55
	s_mov_b32 s10, s11
	s_cbranch_scc0 .LBB0_331

; #define PG8_STAGE(bufoff, gbase, voff) do { _Pragma("unroll") for (int _i = 0; _i < 2; ++_i) \
;         __builtin_amdgcn_global_load_lds((const unsigned*)((const char*)(gbase) + (voff)[_i]), (LAS unsigned*)(lds + (bufoff) + ldsw + _i * 8192), 16, 0, 0); } while (0)
; #define PG8_LDA(dst, b, h) do { _Pragma("unroll") for (int m = 0; m < 4; ++m) _Pragma("unroll") for (int k = 0; k < 2; ++k) dst[m][k] = *(const LAS bf16x8*)(lds + PG8_SA(b, h) + aoff + m * 2048 + k * 1024); } while (0)
; #define PG8_LDB(dst, b, h) do { _Pragma("unroll") for (int n = 0; n < 2; ++n) _Pragma("unroll") for (int k = 0; k < 2; ++k) dst[n][k] = *(const LAS bf16x8*)(lds + PG8_SB(b, h) + boff + n * 2048 + k * 1024); } while (0)
; #define PG8_MMA(ai, bj, At, Bt) do { __builtin_amdgcn_s_setprio(1); _Pragma("unroll") for (int k = 0; k < 2; ++k) _Pragma("unroll") for (int m = 0; m < 4; ++m) _Pragma("unroll") for (int n = 0; n < 2; ++n) \
;         acc[ai][bj][m][n] = __builtin_amdgcn_mfma_f32_16x16x32_bf16(Bt[n][k], At[m][k], acc[ai][bj][m][n], 0, 0, 0); __builtin_amdgcn_s_setprio(0); } while (0)
; #define PG8_WAIT_V(n) asm volatile("s_waitcnt vmcnt(" #n ")" ::: "memory")
; #define PG8_WAIT_L(n) asm volatile("s_waitcnt lgkmcnt(" #n ")" ::: "memory")
; #define PG8_BAR __builtin_amdgcn_s_barrier()
; #define PG8_SCHED __builtin_amdgcn_sched_barrier(0)
; template <class Epi, bool ALIGN_EPI>
; __device__ __forceinline__ void gemm_phase(LAS unsigned char* lds, const Gemm g, const StaticOrder& S, const Epi& E, const int tid) {
;     ...
;             const bool last = (t == nt - 2);
;             const char* a1 = cA + (size_t)(t + 1) * kstep;
;             const char* a2 = last ? nA : cA + (size_t)(t + 2) * kstep; const char* b2 = last ? nB : cB + (size_t)(t + 2) * kstep;
;             const char* a3 = a2 + kstep; const char* b3 = b2 + kstep;
;             PG8_LDB(B0, 0, 0); PG8_LDB(B1, 0, 1); PG8_SCHED; PG8_LDA(At, 0, 0); PG8_STAGE(PG8_SA(1, 1), a1 + hA, voffA);
;             PG8_WAIT_V(8); PG8_WAIT_L(0); PG8_BAR; PG8_MMA(0, 0, At, B0); PG8_MMA(0, 1, At, B1); PG8_BAR; PG8_SCHED;
;             PG8_LDA(At, 0, 1); PG8_STAGE(PG8_SB(0, 0), b2, voffB); PG8_STAGE(PG8_SB(0, 1), b2 + hB, voffB); PG8_STAGE(PG8_SA(0, 0), a2, voffA);
;             PG8_WAIT_V(8); PG8_WAIT_L(0); PG8_BAR; PG8_MMA(1, 0, At, B0); PG8_MMA(1, 1, At, B1); PG8_BAR; PG8_SCHED;
.LBB0_354:
	s_add_i32 s11, s10, 2
	s_cmp_eq_u32 s55, s10
	s_cselect_b64 vcc, -1, 0
	v_add_u32_e32 v148, s33, v149
	s_add_i32 s10, 0, 0x14000
	ds_read_b128 v[152:155], v148
	ds_read_b128 v[156:159], v148 offset:1024
	ds_read_b128 v[160:163], v148 offset:2048
	ds_read_b128 v[164:167], v148 offset:3072
	v_add_u32_e32 v148, s10, v149
	ds_read_b128 v[176:179], v148
	ds_read_b128 v[180:183], v148 offset:1024
	ds_read_b128 v[184:187], v148 offset:2048
	ds_read_b128 v[188:191], v148 offset:3072
	v_lshl_add_u64 v[146:147], v[142:143], 0, s[92:93]
	v_cndmask_b32_e32 v147, v147, v139, vcc
	v_cndmask_b32_e32 v146, v146, v138, vcc
	v_cndmask_b32_e32 v221, v145, v141, vcc
	v_cndmask_b32_e32 v220, v144, v140, vcc
	v_lshl_add_u64 v[244:245], v[142:143], 0, v[134:135]
	s_add_i32 m0, s25, 0xc000
	ds_read_b128 v[192:195], v151
	ds_read_b128 v[196:199], v151 offset:1024
	ds_read_b128 v[200:203], v151 offset:2048
	ds_read_b128 v[204:207], v151 offset:3072
	ds_read_b128 v[208:211], v151 offset:4096
	ds_read_b128 v[212:215], v151 offset:5120
	ds_read_b128 v[216:219], v151 offset:6144
	ds_read_b128 v[240:243], v151 offset:7168
	global_load_lds_dwordx4 v[244:245], off
	v_lshl_add_u64 v[244:245], v[142:143], 0, v[136:137]
	s_add_i32 m0, s25, 0xe000
	s_nop 0
	global_load_lds_dwordx4 v[244:245], off
	s_waitcnt vmcnt(8)
	s_waitcnt lgkmcnt(0)
	s_barrier
	s_setprio 1
	s_waitcnt lgkmcnt(0)
	v_mfma_f32_16x16x32_bf16 v[124:127], v[152:155], v[192:195], v[124:127]
	v_mfma_f32_16x16x32_bf16 v[120:123], v[160:163], v[192:195], v[120:123]
	v_mfma_f32_16x16x32_bf16 v[108:111], v[152:155], v[200:203], v[108:111]
	v_mfma_f32_16x16x32_bf16 v[104:107], v[160:163], v[200:203], v[104:107]
	v_mfma_f32_16x16x32_bf16 v[92:95], v[152:155], v[208:211], v[92:95]
	v_mfma_f32_16x16x32_bf16 v[88:91], v[160:163], v[208:211], v[88:91]
	v_mfma_f32_16x16x32_bf16 v[76:79], v[152:155], v[216:219], v[76:79]
	v_mfma_f32_16x16x32_bf16 v[72:75], v[160:163], v[216:219], v[72:75]
	v_mfma_f32_16x16x32_bf16 v[124:127], v[156:159], v[196:199], v[124:127]
	v_mfma_f32_16x16x32_bf16 v[120:123], v[164:167], v[196:199], v[120:123]
	v_mfma_f32_16x16x32_bf16 v[108:111], v[156:159], v[204:207], v[108:111]
	v_mfma_f32_16x16x32_bf16 v[104:107], v[164:167], v[204:207], v[104:107]
	v_mfma_f32_16x16x32_bf16 v[92:95], v[156:159], v[212:215], v[92:95]
	v_mfma_f32_16x16x32_bf16 v[88:91], v[164:167], v[212:215], v[88:91]
	v_mfma_f32_16x16x32_bf16 v[76:79], v[156:159], v[240:243], v[76:79]
	v_mfma_f32_16x16x32_bf16 v[72:75], v[164:167], v[240:243], v[72:75]
	v_mfma_f32_16x16x32_bf16 v[116:119], v[176:179], v[192:195], v[116:119]
	v_mfma_f32_16x16x32_bf16 v[112:115], v[184:187], v[192:195], v[112:115]
	v_mfma_f32_16x16x32_bf16 v[100:103], v[176:179], v[200:203], v[100:103]
	v_mfma_f32_16x16x32_bf16 v[96:99], v[184:187], v[200:203], v[96:99]
	v_mfma_f32_16x16x32_bf16 v[84:87], v[176:179], v[208:211], v[84:87]
	v_mfma_f32_16x16x32_bf16 v[80:83], v[184:187], v[208:211], v[80:83]
	v_mfma_f32_16x16x32_bf16 v[68:71], v[176:179], v[216:219], v[68:71]
	v_mfma_f32_16x16x32_bf16 v[64:67], v[184:187], v[216:219], v[64:67]
	v_mfma_f32_16x16x32_bf16 v[116:119], v[180:183], v[196:199], v[116:119]
	v_mfma_f32_16x16x32_bf16 v[112:115], v[188:191], v[196:199], v[112:115]
	v_mfma_f32_16x16x32_bf16 v[100:103], v[180:183], v[204:207], v[100:103]
	v_mfma_f32_16x16x32_bf16 v[96:99], v[188:191], v[204:207], v[96:99]
	v_mfma_f32_16x16x32_bf16 v[84:87], v[180:183], v[212:215], v[84:87]
	v_mfma_f32_16x16x32_bf16 v[80:83], v[188:191], v[212:215], v[80:83]
	v_mfma_f32_16x16x32_bf16 v[68:71], v[180:183], v[240:243], v[68:71]
	v_mfma_f32_16x16x32_bf16 v[64:67], v[188:191], v[240:243], v[64:67]
	s_setprio 0
	s_barrier
	s_add_i32 s62, s33, s45
	v_lshl_add_u64 v[244:245], v[220:221], 0, v[168:169]
	s_mov_b32 m0, s62
	ds_read_b128 v[192:195], v151 offset:16384
	ds_read_b128 v[196:199], v151 offset:17408
	ds_read_b128 v[200:203], v151 offset:18432
	ds_read_b128 v[204:207], v151 offset:19456
	ds_read_b128 v[208:211], v151 offset:20480
	ds_read_b128 v[212:215], v151 offset:21504
	ds_read_b128 v[216:219], v151 offset:22528
	ds_read_b128 v[240:243], v151 offset:23552
	global_load_lds_dwordx4 v[244:245], off
	v_lshl_add_u64 v[246:247], v[220:221], 0, v[128:129]
	s_add_i32 m0, s62, 0x2000
	v_lshl_add_u64 v[220:221], v[220:221], 0, s[12:13]
	s_add_i32 s10, s10, s45
	global_load_lds_dwordx4 v[246:247], off
	v_lshl_add_u64 v[248:249], v[220:221], 0, v[168:169]
	s_mov_b32 m0, s10
	v_lshl_add_u64 v[220:221], v[220:221], 0, v[128:129]
	global_load_lds_dwordx4 v[248:249], off
	s_add_i32 m0, s10, 0x2000
	v_lshl_add_u64 v[250:251], v[146:147], 0, v[132:133]
	global_load_lds_dwordx4 v[220:221], off
	s_mov_b32 m0, s25
	v_lshl_add_u64 v[252:253], v[146:147], 0, v[130:131]
	global_load_lds_dwordx4 v[250:251], off
	s_mov_b32 m0, s50
	s_nop 0
	global_load_lds_dwordx4 v[252:253], off
	s_waitcnt vmcnt(8)
	s_waitcnt lgkmcnt(0)
	s_barrier
; #define PG8_STAGE(bufoff, gbase, voff) do { _Pragma("unroll") for (int _i = 0; _i < 2; ++_i) \
;         __builtin_amdgcn_global_load_lds((const unsigned*)((const char*)(gbase) + (voff)[_i]), (LAS unsigned*)(lds + (bufoff) + ldsw + _i * 8192), 16, 0, 0); } while (0)
; #define PG8_LDA(dst, b, h) do { _Pragma("unroll") for (int m = 0; m < 4; ++m) _Pragma("unroll") for (int k = 0; k < 2; ++k) dst[m][k] = *(const LAS bf16x8*)(lds + PG8_SA(b, h) + aoff + m * 2048 + k * 1024); } while (0)
; #define PG8_LDB(dst, b, h) do { _Pragma("unroll") for (int n = 0; n < 2; ++n) _Pragma("unroll") for (int k = 0; k < 2; ++k) dst[n][k] = *(const LAS bf16x8*)(lds + PG8_SB(b, h) + boff + n * 2048 + k * 1024); } while (0)
; #define PG8_MMA(ai, bj, At, Bt) do { __builtin_amdgcn_s_setprio(1); _Pragma("unroll") for (int k = 0; k < 2; ++k) _Pragma("unroll") for (int m = 0; m < 4; ++m) _Pragma("unroll") for (int n = 0; n < 2; ++n) \
;         acc[ai][bj][m][n] = __builtin_amdgcn_mfma_f32_16x16x32_bf16(Bt[n][k], At[m][k], acc[ai][bj][m][n], 0, 0, 0); __builtin_amdgcn_s_setprio(0); } while (0)
; #define PG8_WAIT_V(n) asm volatile("s_waitcnt vmcnt(" #n ")" ::: "memory")
; #define PG8_WAIT_L(n) asm volatile("s_waitcnt lgkmcnt(" #n ")" ::: "memory")
; #define PG8_BAR __builtin_amdgcn_s_barrier()
; #define PG8_SCHED __builtin_amdgcn_sched_barrier(0)
; template <class Epi, bool ALIGN_EPI>
; __device__ __forceinline__ void gemm_phase(LAS unsigned char* lds, const Gemm g, const StaticOrder& S, const Epi& E, const int tid) {
;     ...
;             PG8_WAIT_V(8); PG8_WAIT_L(0); PG8_BAR; PG8_MMA(1, 0, At, B0); PG8_MMA(1, 1, At, B1); PG8_BAR; PG8_SCHED;
;             PG8_LDB(B0, 1, 0); PG8_LDB(B1, 1, 1); PG8_SCHED; PG8_LDA(At, 1, 0); PG8_STAGE(PG8_SA(0, 1), a2 + hA, voffA);
;             PG8_WAIT_V(8); PG8_WAIT_L(0); PG8_BAR; PG8_MMA(0, 0, At, B0); PG8_MMA(0, 1, At, B1); PG8_BAR; PG8_SCHED;
	s_setprio 1
	s_waitcnt lgkmcnt(0)
	v_mfma_f32_16x16x32_bf16 v[60:63], v[152:155], v[192:195], v[60:63]
	v_mfma_f32_16x16x32_bf16 v[56:59], v[160:163], v[192:195], v[56:59]
	v_mfma_f32_16x16x32_bf16 v[44:47], v[152:155], v[200:203], v[44:47]
	v_mfma_f32_16x16x32_bf16 v[40:43], v[160:163], v[200:203], v[40:43]
	v_mfma_f32_16x16x32_bf16 v[28:31], v[152:155], v[208:211], v[28:31]
	v_mfma_f32_16x16x32_bf16 v[24:27], v[160:163], v[208:211], v[24:27]
	v_mfma_f32_16x16x32_bf16 v[12:15], v[152:155], v[216:219], v[12:15]
	v_mfma_f32_16x16x32_bf16 v[8:11], v[160:163], v[216:219], v[8:11]
	v_mfma_f32_16x16x32_bf16 v[60:63], v[156:159], v[196:199], v[60:63]
	v_mfma_f32_16x16x32_bf16 v[56:59], v[164:167], v[196:199], v[56:59]
	v_mfma_f32_16x16x32_bf16 v[44:47], v[156:159], v[204:207], v[44:47]
	v_mfma_f32_16x16x32_bf16 v[40:43], v[164:167], v[204:207], v[40:43]
	v_mfma_f32_16x16x32_bf16 v[28:31], v[156:159], v[212:215], v[28:31]
	v_mfma_f32_16x16x32_bf16 v[24:27], v[164:167], v[212:215], v[24:27]
	v_mfma_f32_16x16x32_bf16 v[12:15], v[156:159], v[240:243], v[12:15]
	v_mfma_f32_16x16x32_bf16 v[8:11], v[164:167], v[240:243], v[8:11]
	v_mfma_f32_16x16x32_bf16 v[52:55], v[176:179], v[192:195], v[52:55]
	v_mfma_f32_16x16x32_bf16 v[48:51], v[184:187], v[192:195], v[48:51]
	v_mfma_f32_16x16x32_bf16 v[36:39], v[176:179], v[200:203], v[36:39]
	v_mfma_f32_16x16x32_bf16 v[32:35], v[184:187], v[200:203], v[32:35]
	v_mfma_f32_16x16x32_bf16 v[20:23], v[176:179], v[208:211], v[20:23]
	v_mfma_f32_16x16x32_bf16 v[16:19], v[184:187], v[208:211], v[16:19]
	v_mfma_f32_16x16x32_bf16 v[4:7], v[176:179], v[216:219], v[4:7]
	v_mfma_f32_16x16x32_bf16 v[0:3], v[184:187], v[216:219], v[0:3]
	v_mfma_f32_16x16x32_bf16 v[52:55], v[180:183], v[196:199], v[52:55]
	v_mfma_f32_16x16x32_bf16 v[48:51], v[188:191], v[196:199], v[48:51]
	v_mfma_f32_16x16x32_bf16 v[36:39], v[180:183], v[204:207], v[36:39]
	v_mfma_f32_16x16x32_bf16 v[32:35], v[188:191], v[204:207], v[32:35]
	v_mfma_f32_16x16x32_bf16 v[20:23], v[180:183], v[212:215], v[20:23]
	v_mfma_f32_16x16x32_bf16 v[16:19], v[188:191], v[212:215], v[16:19]
	v_mfma_f32_16x16x32_bf16 v[4:7], v[180:183], v[240:243], v[4:7]
	v_mfma_f32_16x16x32_bf16 v[0:3], v[188:191], v[240:243], v[0:3]
	s_setprio 0
	s_barrier
	s_add_i32 s10, 0, 0x18000
	v_add_u32_e32 v148, s10, v149
	s_add_i32 s62, 0, 0x1c000
	ds_read_b128 v[152:155], v148
	ds_read_b128 v[156:159], v148 offset:1024
	ds_read_b128 v[160:163], v148 offset:2048
	ds_read_b128 v[164:167], v148 offset:3072
	v_add_u32_e32 v148, s62, v149
	ds_read_b128 v[176:179], v148
	ds_read_b128 v[180:183], v148 offset:1024
	ds_read_b128 v[184:187], v148 offset:2048
	ds_read_b128 v[188:191], v148 offset:3072
	v_lshl_add_u64 v[146:147], v[146:147], 0, s[94:95]
	s_mov_b32 m0, s51
	v_lshl_add_u64 v[226:227], v[146:147], 0, v[132:133]
	ds_read_b128 v[192:195], v151 offset:32768
	ds_read_b128 v[196:199], v151 offset:33792
	ds_read_b128 v[200:203], v151 offset:34816
	ds_read_b128 v[204:207], v151 offset:35840
	ds_read_b128 v[208:211], v151 offset:36864
	ds_read_b128 v[212:215], v151 offset:37888
	ds_read_b128 v[216:219], v151 offset:38912
	ds_read_b128 v[240:243], v151 offset:39936
	global_load_lds_dwordx4 v[226:227], off
	v_lshl_add_u64 v[146:147], v[146:147], 0, v[130:131]
	s_mov_b32 m0, s52
	s_nop 0
	global_load_lds_dwordx4 v[146:147], off
	s_waitcnt vmcnt(8)
	s_waitcnt lgkmcnt(0)
	s_barrier
	s_setprio 1
	s_waitcnt lgkmcnt(0)
	v_mfma_f32_16x16x32_bf16 v[124:127], v[152:155], v[192:195], v[124:127]
	v_mfma_f32_16x16x32_bf16 v[120:123], v[160:163], v[192:195], v[120:123]
	v_mfma_f32_16x16x32_bf16 v[108:111], v[152:155], v[200:203], v[108:111]
	v_mfma_f32_16x16x32_bf16 v[104:107], v[160:163], v[200:203], v[104:107]
	v_mfma_f32_16x16x32_bf16 v[92:95], v[152:155], v[208:211], v[92:95]
	v_mfma_f32_16x16x32_bf16 v[88:91], v[160:163], v[208:211], v[88:91]
	v_mfma_f32_16x16x32_bf16 v[76:79], v[152:155], v[216:219], v[76:79]
	v_mfma_f32_16x16x32_bf16 v[72:75], v[160:163], v[216:219], v[72:75]
	v_mfma_f32_16x16x32_bf16 v[124:127], v[156:159], v[196:199], v[124:127]
	v_mfma_f32_16x16x32_bf16 v[120:123], v[164:167], v[196:199], v[120:123]
	v_mfma_f32_16x16x32_bf16 v[108:111], v[156:159], v[204:207], v[108:111]
	v_mfma_f32_16x16x32_bf16 v[104:107], v[164:167], v[204:207], v[104:107]
	v_mfma_f32_16x16x32_bf16 v[92:95], v[156:159], v[212:215], v[92:95]
	v_mfma_f32_16x16x32_bf16 v[88:91], v[164:167], v[212:215], v[88:91]
	v_mfma_f32_16x16x32_bf16 v[76:79], v[156:159], v[240:243], v[76:79]
	v_mfma_f32_16x16x32_bf16 v[72:75], v[164:167], v[240:243], v[72:75]
	v_mfma_f32_16x16x32_bf16 v[116:119], v[176:179], v[192:195], v[116:119]
	v_mfma_f32_16x16x32_bf16 v[112:115], v[184:187], v[192:195], v[112:115]
	v_mfma_f32_16x16x32_bf16 v[100:103], v[176:179], v[200:203], v[100:103]
	v_mfma_f32_16x16x32_bf16 v[96:99], v[184:187], v[200:203], v[96:99]
	v_mfma_f32_16x16x32_bf16 v[84:87], v[176:179], v[208:211], v[84:87]
	v_mfma_f32_16x16x32_bf16 v[80:83], v[184:187], v[208:211], v[80:83]
	v_mfma_f32_16x16x32_bf16 v[68:71], v[176:179], v[216:219], v[68:71]
	v_mfma_f32_16x16x32_bf16 v[64:67], v[184:187], v[216:219], v[64:67]
	v_mfma_f32_16x16x32_bf16 v[116:119], v[180:183], v[196:199], v[116:119]
	v_mfma_f32_16x16x32_bf16 v[112:115], v[188:191], v[196:199], v[112:115]
	v_mfma_f32_16x16x32_bf16 v[100:103], v[180:183], v[204:207], v[100:103]
	v_mfma_f32_16x16x32_bf16 v[96:99], v[188:191], v[204:207], v[96:99]
	v_mfma_f32_16x16x32_bf16 v[84:87], v[180:183], v[212:215], v[84:87]
	v_mfma_f32_16x16x32_bf16 v[80:83], v[188:191], v[212:215], v[80:83]
	v_mfma_f32_16x16x32_bf16 v[68:71], v[180:183], v[240:243], v[68:71]
	v_mfma_f32_16x16x32_bf16 v[64:67], v[188:191], v[240:243], v[64:67]
	s_setprio 0
	s_barrier
; #define PG8_STAGE(bufoff, gbase, voff) do { _Pragma("unroll") for (int _i = 0; _i < 2; ++_i) \
;         __builtin_amdgcn_global_load_lds((const unsigned*)((const char*)(gbase) + (voff)[_i]), (LAS unsigned*)(lds + (bufoff) + ldsw + _i * 8192), 16, 0, 0); } while (0)
; #define PG8_LDA(dst, b, h) do { _Pragma("unroll") for (int m = 0; m < 4; ++m) _Pragma("unroll") for (int k = 0; k < 2; ++k) dst[m][k] = *(const LAS bf16x8*)(lds + PG8_SA(b, h) + aoff + m * 2048 + k * 1024); } while (0)
; #define PG8_MMA(ai, bj, At, Bt) do { __builtin_amdgcn_s_setprio(1); _Pragma("unroll") for (int k = 0; k < 2; ++k) _Pragma("unroll") for (int m = 0; m < 4; ++m) _Pragma("unroll") for (int n = 0; n < 2; ++n) \
;         acc[ai][bj][m][n] = __builtin_amdgcn_mfma_f32_16x16x32_bf16(Bt[n][k], At[m][k], acc[ai][bj][m][n], 0, 0, 0); __builtin_amdgcn_s_setprio(0); } while (0)
; #define PG8_WAIT_V(n) asm volatile("s_waitcnt vmcnt(" #n ")" ::: "memory")
; #define PG8_WAIT_L(n) asm volatile("s_waitcnt lgkmcnt(" #n ")" ::: "memory")
; #define PG8_BAR __builtin_amdgcn_s_barrier()
; #define PG8_SCHED __builtin_amdgcn_sched_barrier(0)
; template <class Epi, bool ALIGN_EPI>
; __device__ __forceinline__ void gemm_phase(LAS unsigned char* lds, const Gemm g, const StaticOrder& S, const Epi& E, const int tid) {
;     ...
;             PG8_LDA(At, 1, 1); PG8_STAGE(PG8_SB(1, 0), b3, voffB); PG8_STAGE(PG8_SB(1, 1), b3 + hB, voffB); PG8_STAGE(PG8_SA(1, 0), a3, voffA);
;             PG8_WAIT_V(8); PG8_WAIT_L(0); PG8_BAR; PG8_MMA(1, 0, At, B0); PG8_MMA(1, 1, At, B1); PG8_BAR; PG8_SCHED;
;         }
	s_add_i32 s10, s10, s45
	v_lshl_add_u64 v[146:147], v[244:245], 0, s[92:93]
	s_mov_b32 m0, s10
	ds_read_b128 v[192:195], v151 offset:49152
	ds_read_b128 v[196:199], v151 offset:50176
	ds_read_b128 v[200:203], v151 offset:51200
	ds_read_b128 v[204:207], v151 offset:52224
	ds_read_b128 v[208:211], v151 offset:53248
	ds_read_b128 v[212:215], v151 offset:54272
	ds_read_b128 v[216:219], v151 offset:55296
	ds_read_b128 v[240:243], v151 offset:56320
	global_load_lds_dwordx4 v[146:147], off
	v_lshl_add_u64 v[146:147], v[246:247], 0, s[92:93]
	s_add_i32 m0, s10, 0x2000
	s_add_i32 s10, s62, s45
	global_load_lds_dwordx4 v[146:147], off
	v_lshl_add_u64 v[146:147], v[248:249], 0, s[92:93]
	s_mov_b32 m0, s10
	s_nop 0
	global_load_lds_dwordx4 v[146:147], off
	v_lshl_add_u64 v[146:147], v[220:221], 0, s[92:93]
	s_add_i32 m0, s10, 0x2000
	s_nop 0
	global_load_lds_dwordx4 v[146:147], off
	v_lshl_add_u64 v[146:147], v[250:251], 0, s[92:93]
	s_mov_b32 m0, s53
	s_nop 0
	global_load_lds_dwordx4 v[146:147], off
	v_lshl_add_u64 v[146:147], v[252:253], 0, s[92:93]
	s_mov_b32 m0, s54
	s_nop 0
	global_load_lds_dwordx4 v[146:147], off
	s_waitcnt vmcnt(8)
	s_waitcnt lgkmcnt(0)
	s_barrier
	s_setprio 1
	s_waitcnt lgkmcnt(0)
	v_mfma_f32_16x16x32_bf16 v[60:63], v[152:155], v[192:195], v[60:63]
	v_mfma_f32_16x16x32_bf16 v[56:59], v[160:163], v[192:195], v[56:59]
	v_mfma_f32_16x16x32_bf16 v[44:47], v[152:155], v[200:203], v[44:47]
	v_mfma_f32_16x16x32_bf16 v[40:43], v[160:163], v[200:203], v[40:43]
	v_mfma_f32_16x16x32_bf16 v[28:31], v[152:155], v[208:211], v[28:31]
	v_mfma_f32_16x16x32_bf16 v[24:27], v[160:163], v[208:211], v[24:27]
	v_mfma_f32_16x16x32_bf16 v[12:15], v[152:155], v[216:219], v[12:15]
	v_mfma_f32_16x16x32_bf16 v[8:11], v[160:163], v[216:219], v[8:11]
	v_mfma_f32_16x16x32_bf16 v[60:63], v[156:159], v[196:199], v[60:63]
	v_mfma_f32_16x16x32_bf16 v[56:59], v[164:167], v[196:199], v[56:59]
	v_mfma_f32_16x16x32_bf16 v[44:47], v[156:159], v[204:207], v[44:47]
	v_mfma_f32_16x16x32_bf16 v[40:43], v[164:167], v[204:207], v[40:43]
	v_mfma_f32_16x16x32_bf16 v[28:31], v[156:159], v[212:215], v[28:31]
	v_mfma_f32_16x16x32_bf16 v[24:27], v[164:167], v[212:215], v[24:27]
	v_mfma_f32_16x16x32_bf16 v[12:15], v[156:159], v[240:243], v[12:15]
	v_mfma_f32_16x16x32_bf16 v[8:11], v[164:167], v[240:243], v[8:11]
	v_mfma_f32_16x16x32_bf16 v[52:55], v[176:179], v[192:195], v[52:55]
	v_mfma_f32_16x16x32_bf16 v[48:51], v[184:187], v[192:195], v[48:51]
	v_mfma_f32_16x16x32_bf16 v[36:39], v[176:179], v[200:203], v[36:39]
	v_mfma_f32_16x16x32_bf16 v[32:35], v[184:187], v[200:203], v[32:35]
	v_mfma_f32_16x16x32_bf16 v[20:23], v[176:179], v[208:211], v[20:23]
	v_mfma_f32_16x16x32_bf16 v[16:19], v[184:187], v[208:211], v[16:19]
	v_mfma_f32_16x16x32_bf16 v[4:7], v[176:179], v[216:219], v[4:7]
	v_mfma_f32_16x16x32_bf16 v[0:3], v[184:187], v[216:219], v[0:3]
	v_mfma_f32_16x16x32_bf16 v[52:55], v[180:183], v[196:199], v[52:55]
	v_mfma_f32_16x16x32_bf16 v[48:51], v[188:191], v[196:199], v[48:51]
	v_mfma_f32_16x16x32_bf16 v[36:39], v[180:183], v[204:207], v[36:39]
	v_mfma_f32_16x16x32_bf16 v[32:35], v[188:191], v[204:207], v[32:35]
	v_mfma_f32_16x16x32_bf16 v[20:23], v[180:183], v[212:215], v[20:23]
	v_mfma_f32_16x16x32_bf16 v[16:19], v[188:191], v[212:215], v[16:19]
	v_mfma_f32_16x16x32_bf16 v[4:7], v[180:183], v[240:243], v[4:7]
	v_mfma_f32_16x16x32_bf16 v[0:3], v[188:191], v[240:243], v[0:3]
	s_setprio 0
	s_barrier
	v_lshl_add_u64 v[142:143], v[142:143], 0, s[80:81]
	v_lshl_add_u64 v[144:145], v[144:145], 0, s[80:81]
	s_cmp_ge_u32 s11, s1
	s_mov_b32 s10, s11
	s_cbranch_scc0 .LBB0_354

; #define PG8_STAGE(bufoff, gbase, voff) do { _Pragma("unroll") for (int _i = 0; _i < 2; ++_i) \
;         __builtin_amdgcn_global_load_lds((const unsigned*)((const char*)(gbase) + (voff)[_i]), (LAS unsigned*)(lds + (bufoff) + ldsw + _i * 8192), 16, 0, 0); } while (0)
; #define PG8_LDA(dst, b, h) do { _Pragma("unroll") for (int m = 0; m < 4; ++m) _Pragma("unroll") for (int k = 0; k < 2; ++k) dst[m][k] = *(const LAS bf16x8*)(lds + PG8_SA(b, h) + aoff + m * 2048 + k * 1024); } while (0)
; #define PG8_LDB(dst, b, h) do { _Pragma("unroll") for (int n = 0; n < 2; ++n) _Pragma("unroll") for (int k = 0; k < 2; ++k) dst[n][k] = *(const LAS bf16x8*)(lds + PG8_SB(b, h) + boff + n * 2048 + k * 1024); } while (0)
; #define PG8_MMA(ai, bj, At, Bt) do { __builtin_amdgcn_s_setprio(1); _Pragma("unroll") for (int k = 0; k < 2; ++k) _Pragma("unroll") for (int m = 0; m < 4; ++m) _Pragma("unroll") for (int n = 0; n < 2; ++n) \
;         acc[ai][bj][m][n] = __builtin_amdgcn_mfma_f32_16x16x32_bf16(Bt[n][k], At[m][k], acc[ai][bj][m][n], 0, 0, 0); __builtin_amdgcn_s_setprio(0); } while (0)
; #define PG8_WAIT_V(n) asm volatile("s_waitcnt vmcnt(" #n ")" ::: "memory")
; #define PG8_WAIT_L(n) asm volatile("s_waitcnt lgkmcnt(" #n ")" ::: "memory")
; #define PG8_BAR __builtin_amdgcn_s_barrier()
; #define PG8_SCHED __builtin_amdgcn_sched_barrier(0)
; template <class Epi, bool ALIGN_EPI>
; __device__ __forceinline__ void gemm_phase(LAS unsigned char* lds, const Gemm g, const StaticOrder& S, const Epi& E, const int tid) {
;     ...
;             const bool last = (t == nt - 2);
;             const char* a1 = cA + (size_t)(t + 1) * kstep;
;             const char* a2 = last ? nA : cA + (size_t)(t + 2) * kstep; const char* b2 = last ? nB : cB + (size_t)(t + 2) * kstep;
;             const char* a3 = a2 + kstep; const char* b3 = b2 + kstep;
;             PG8_LDB(B0, 0, 0); PG8_LDB(B1, 0, 1); PG8_SCHED; PG8_LDA(At, 0, 0); PG8_STAGE(PG8_SA(1, 1), a1 + hA, voffA);
;             PG8_WAIT_V(8); PG8_WAIT_L(0); PG8_BAR; PG8_MMA(0, 0, At, B0); PG8_MMA(0, 1, At, B1); PG8_BAR; PG8_SCHED;
;             PG8_LDA(At, 0, 1); PG8_STAGE(PG8_SB(0, 0), b2, voffB); PG8_STAGE(PG8_SB(0, 1), b2 + hB, voffB); PG8_STAGE(PG8_SA(0, 0), a2, voffA);
;             PG8_WAIT_V(8); PG8_WAIT_L(0); PG8_BAR; PG8_MMA(1, 0, At, B0); PG8_MMA(1, 1, At, B1); PG8_BAR; PG8_SCHED;
.LBB0_379:
	s_add_u32 s41, s34, s40
	s_addc_u32 s46, s35, 0
	s_add_u32 s44, s41, 0x100
	s_addc_u32 s45, s46, 0
	s_and_b64 s[42:43], s[38:39], exec
	s_cselect_b32 s43, s17, s45
	s_cselect_b32 s42, s59, s44
	s_add_u32 s40, s30, s40
	s_addc_u32 s44, s31, 0
	s_add_u32 s40, s40, 0x100
	s_addc_u32 s44, s44, 0
	s_and_b64 s[38:39], s[38:39], exec
	s_cselect_b32 s45, s15, s44
	s_cselect_b32 s44, s60, s40
	s_add_i32 s39, 0, 0x14000
	s_add_u32 s48, s41, 0x10080
	s_addc_u32 s49, s46, 0
	s_add_i32 s68, s33, s50
	s_add_i32 m0, s51, 0xc000
	s_add_i32 s71, s51, 0xe000
	s_add_i32 s65, s68, 0x2000
	v_add_u32_e32 v138, s33, v141
	s_add_u32 s46, s44, 0x10000
	ds_read_b128 v[134:137], v138
	ds_read_b128 v[146:149], v138 offset:1024
	ds_read_b128 v[150:153], v138 offset:2048
	ds_read_b128 v[154:157], v138 offset:3072
	v_add_u32_e32 v138, s39, v141
	s_addc_u32 s47, s45, 0
	s_add_i32 s67, s39, s50
	ds_read_b128 v[158:161], v138
	ds_read_b128 v[162:165], v138 offset:1024
	ds_read_b128 v[174:177], v138 offset:2048
	ds_read_b128 v[178:181], v138 offset:3072
	s_add_i32 s66, s67, 0x2000
	s_add_i32 s64, 0, 0x18000
	s_add_i32 s63, 0, 0x1c000
	s_add_u32 s40, s42, 0x10000
	s_addc_u32 s41, s43, 0
	s_add_i32 s62, s64, s50
	s_add_i32 s61, s62, 0x2000
	s_add_u32 s38, s44, 0x10080
	s_addc_u32 s39, s45, 0
	s_add_i32 s70, s63, s50
	s_add_i32 s69, s70, 0x2000
	v_lshl_add_u64 v[138:139], s[48:49], 0, v[128:129]
	ds_read_b128 v[182:185], v145
	ds_read_b128 v[186:189], v145 offset:1024
	ds_read_b128 v[190:193], v145 offset:2048
	ds_read_b128 v[194:197], v145 offset:3072
	ds_read_b128 v[198:201], v145 offset:4096
	ds_read_b128 v[202:205], v145 offset:5120
	ds_read_b128 v[206:209], v145 offset:6144
	ds_read_b128 v[210:213], v145 offset:7168
	global_load_lds_dwordx4 v[138:139], off
	v_lshl_add_u64 v[138:139], s[48:49], 0, v[130:131]
	s_mov_b32 m0, s71
	s_nop 0
	global_load_lds_dwordx4 v[138:139], off
	s_waitcnt vmcnt(8)
	s_waitcnt lgkmcnt(0)
	s_barrier
	s_setprio 1
	s_waitcnt lgkmcnt(0)
	v_mfma_f32_16x16x32_bf16 v[124:127], v[134:137], v[182:185], v[124:127]
	v_mfma_f32_16x16x32_bf16 v[120:123], v[150:153], v[182:185], v[120:123]
	v_mfma_f32_16x16x32_bf16 v[108:111], v[134:137], v[190:193], v[108:111]
	v_mfma_f32_16x16x32_bf16 v[104:107], v[150:153], v[190:193], v[104:107]
	v_mfma_f32_16x16x32_bf16 v[92:95], v[134:137], v[198:201], v[92:95]
	v_mfma_f32_16x16x32_bf16 v[88:91], v[150:153], v[198:201], v[88:91]
	v_mfma_f32_16x16x32_bf16 v[76:79], v[134:137], v[206:209], v[76:79]
	v_mfma_f32_16x16x32_bf16 v[72:75], v[150:153], v[206:209], v[72:75]
	v_mfma_f32_16x16x32_bf16 v[124:127], v[146:149], v[186:189], v[124:127]
	v_mfma_f32_16x16x32_bf16 v[120:123], v[154:157], v[186:189], v[120:123]
	v_mfma_f32_16x16x32_bf16 v[108:111], v[146:149], v[194:197], v[108:111]
	v_mfma_f32_16x16x32_bf16 v[104:107], v[154:157], v[194:197], v[104:107]
	v_mfma_f32_16x16x32_bf16 v[92:95], v[146:149], v[202:205], v[92:95]
	v_mfma_f32_16x16x32_bf16 v[88:91], v[154:157], v[202:205], v[88:91]
	v_mfma_f32_16x16x32_bf16 v[76:79], v[146:149], v[210:213], v[76:79]
	v_mfma_f32_16x16x32_bf16 v[72:75], v[154:157], v[210:213], v[72:75]
	v_mfma_f32_16x16x32_bf16 v[116:119], v[158:161], v[182:185], v[116:119]
	v_mfma_f32_16x16x32_bf16 v[112:115], v[174:177], v[182:185], v[112:115]
	v_mfma_f32_16x16x32_bf16 v[100:103], v[158:161], v[190:193], v[100:103]
	v_mfma_f32_16x16x32_bf16 v[96:99], v[174:177], v[190:193], v[96:99]
	v_mfma_f32_16x16x32_bf16 v[84:87], v[158:161], v[198:201], v[84:87]
	v_mfma_f32_16x16x32_bf16 v[80:83], v[174:177], v[198:201], v[80:83]
	v_mfma_f32_16x16x32_bf16 v[68:71], v[158:161], v[206:209], v[68:71]
	v_mfma_f32_16x16x32_bf16 v[64:67], v[174:177], v[206:209], v[64:67]
	v_mfma_f32_16x16x32_bf16 v[116:119], v[162:165], v[186:189], v[116:119]
	v_mfma_f32_16x16x32_bf16 v[112:115], v[178:181], v[186:189], v[112:115]
	v_mfma_f32_16x16x32_bf16 v[100:103], v[162:165], v[194:197], v[100:103]
	v_mfma_f32_16x16x32_bf16 v[96:99], v[178:181], v[194:197], v[96:99]
	v_mfma_f32_16x16x32_bf16 v[84:87], v[162:165], v[202:205], v[84:87]
	v_mfma_f32_16x16x32_bf16 v[80:83], v[178:181], v[202:205], v[80:83]
	v_mfma_f32_16x16x32_bf16 v[68:71], v[162:165], v[210:213], v[68:71]
	v_mfma_f32_16x16x32_bf16 v[64:67], v[178:181], v[210:213], v[64:67]
	s_setprio 0
	s_barrier
	s_mov_b32 m0, s68
	v_lshl_add_u64 v[138:139], s[44:45], 0, v[168:169]
	ds_read_b128 v[182:185], v145 offset:16384
	ds_read_b128 v[186:189], v145 offset:17408
	ds_read_b128 v[190:193], v145 offset:18432
	ds_read_b128 v[194:197], v145 offset:19456
	ds_read_b128 v[198:201], v145 offset:20480
	ds_read_b128 v[202:205], v145 offset:21504
	ds_read_b128 v[206:209], v145 offset:22528
	ds_read_b128 v[210:213], v145 offset:23552
	global_load_lds_dwordx4 v[138:139], off
	v_lshl_add_u64 v[142:143], s[44:45], 0, v[132:133]
	s_mov_b32 m0, s65
	v_lshl_add_u64 v[166:167], s[46:47], 0, v[168:169]
	global_load_lds_dwordx4 v[142:143], off
	s_mov_b32 m0, s67
	v_lshl_add_u64 v[214:215], s[42:43], 0, v[130:131]
	global_load_lds_dwordx4 v[166:167], off
	v_lshl_add_u64 v[166:167], s[46:47], 0, v[132:133]
	s_mov_b32 m0, s66
	s_nop 0
	global_load_lds_dwordx4 v[166:167], off
	v_lshl_add_u64 v[166:167], s[42:43], 0, v[128:129]
	s_mov_b32 m0, s51
	s_nop 0
	global_load_lds_dwordx4 v[166:167], off
	s_mov_b32 m0, s52
	s_nop 0
	global_load_lds_dwordx4 v[214:215], off
	s_waitcnt vmcnt(8)
	s_waitcnt lgkmcnt(0)
	s_barrier
; #define PG8_STAGE(bufoff, gbase, voff) do { _Pragma("unroll") for (int _i = 0; _i < 2; ++_i) \
;         __builtin_amdgcn_global_load_lds((const unsigned*)((const char*)(gbase) + (voff)[_i]), (LAS unsigned*)(lds + (bufoff) + ldsw + _i * 8192), 16, 0, 0); } while (0)
; #define PG8_LDA(dst, b, h) do { _Pragma("unroll") for (int m = 0; m < 4; ++m) _Pragma("unroll") for (int k = 0; k < 2; ++k) dst[m][k] = *(const LAS bf16x8*)(lds + PG8_SA(b, h) + aoff + m * 2048 + k * 1024); } while (0)
; #define PG8_LDB(dst, b, h) do { _Pragma("unroll") for (int n = 0; n < 2; ++n) _Pragma("unroll") for (int k = 0; k < 2; ++k) dst[n][k] = *(const LAS bf16x8*)(lds + PG8_SB(b, h) + boff + n * 2048 + k * 1024); } while (0)
; #define PG8_MMA(ai, bj, At, Bt) do { __builtin_amdgcn_s_setprio(1); _Pragma("unroll") for (int k = 0; k < 2; ++k) _Pragma("unroll") for (int m = 0; m < 4; ++m) _Pragma("unroll") for (int n = 0; n < 2; ++n) \
;         acc[ai][bj][m][n] = __builtin_amdgcn_mfma_f32_16x16x32_bf16(Bt[n][k], At[m][k], acc[ai][bj][m][n], 0, 0, 0); __builtin_amdgcn_s_setprio(0); } while (0)
; #define PG8_WAIT_V(n) asm volatile("s_waitcnt vmcnt(" #n ")" ::: "memory")
; #define PG8_WAIT_L(n) asm volatile("s_waitcnt lgkmcnt(" #n ")" ::: "memory")
; #define PG8_BAR __builtin_amdgcn_s_barrier()
; #define PG8_SCHED __builtin_amdgcn_sched_barrier(0)
; template <class Epi, bool ALIGN_EPI>
; __device__ __forceinline__ void gemm_phase(LAS unsigned char* lds, const Gemm g, const StaticOrder& S, const Epi& E, const int tid) {
;     ...
;             PG8_WAIT_V(8); PG8_WAIT_L(0); PG8_BAR; PG8_MMA(1, 0, At, B0); PG8_MMA(1, 1, At, B1); PG8_BAR; PG8_SCHED;
;             PG8_LDB(B0, 1, 0); PG8_LDB(B1, 1, 1); PG8_SCHED; PG8_LDA(At, 1, 0); PG8_STAGE(PG8_SA(0, 1), a2 + hA, voffA);
;             PG8_WAIT_V(8); PG8_WAIT_L(0); PG8_BAR; PG8_MMA(0, 0, At, B0); PG8_MMA(0, 1, At, B1); PG8_BAR; PG8_SCHED;
	s_setprio 1
	s_waitcnt lgkmcnt(0)
	v_mfma_f32_16x16x32_bf16 v[60:63], v[134:137], v[182:185], v[60:63]
	v_mfma_f32_16x16x32_bf16 v[56:59], v[150:153], v[182:185], v[56:59]
	v_mfma_f32_16x16x32_bf16 v[48:51], v[134:137], v[190:193], v[48:51]
	v_mfma_f32_16x16x32_bf16 v[40:43], v[150:153], v[190:193], v[40:43]
	v_mfma_f32_16x16x32_bf16 v[32:35], v[134:137], v[198:201], v[32:35]
	v_mfma_f32_16x16x32_bf16 v[24:27], v[150:153], v[198:201], v[24:27]
	v_mfma_f32_16x16x32_bf16 v[16:19], v[134:137], v[206:209], v[16:19]
	v_mfma_f32_16x16x32_bf16 v[8:11], v[150:153], v[206:209], v[8:11]
	v_mfma_f32_16x16x32_bf16 v[60:63], v[146:149], v[186:189], v[60:63]
	v_mfma_f32_16x16x32_bf16 v[56:59], v[154:157], v[186:189], v[56:59]
	v_mfma_f32_16x16x32_bf16 v[48:51], v[146:149], v[194:197], v[48:51]
	v_mfma_f32_16x16x32_bf16 v[40:43], v[154:157], v[194:197], v[40:43]
	v_mfma_f32_16x16x32_bf16 v[32:35], v[146:149], v[202:205], v[32:35]
	v_mfma_f32_16x16x32_bf16 v[24:27], v[154:157], v[202:205], v[24:27]
	v_mfma_f32_16x16x32_bf16 v[16:19], v[146:149], v[210:213], v[16:19]
	v_mfma_f32_16x16x32_bf16 v[8:11], v[154:157], v[210:213], v[8:11]
	v_mfma_f32_16x16x32_bf16 v[52:55], v[158:161], v[182:185], v[52:55]
	v_mfma_f32_16x16x32_bf16 v[44:47], v[174:177], v[182:185], v[44:47]
	v_mfma_f32_16x16x32_bf16 v[36:39], v[158:161], v[190:193], v[36:39]
	v_mfma_f32_16x16x32_bf16 v[28:31], v[174:177], v[190:193], v[28:31]
	v_mfma_f32_16x16x32_bf16 v[20:23], v[158:161], v[198:201], v[20:23]
	v_mfma_f32_16x16x32_bf16 v[12:15], v[174:177], v[198:201], v[12:15]
	v_mfma_f32_16x16x32_bf16 v[4:7], v[158:161], v[206:209], v[4:7]
	v_mfma_f32_16x16x32_bf16 v[0:3], v[174:177], v[206:209], v[0:3]
	v_mfma_f32_16x16x32_bf16 v[52:55], v[162:165], v[186:189], v[52:55]
	v_mfma_f32_16x16x32_bf16 v[44:47], v[178:181], v[186:189], v[44:47]
	v_mfma_f32_16x16x32_bf16 v[36:39], v[162:165], v[194:197], v[36:39]
	v_mfma_f32_16x16x32_bf16 v[28:31], v[178:181], v[194:197], v[28:31]
	v_mfma_f32_16x16x32_bf16 v[20:23], v[162:165], v[202:205], v[20:23]
	v_mfma_f32_16x16x32_bf16 v[12:15], v[178:181], v[202:205], v[12:15]
	v_mfma_f32_16x16x32_bf16 v[4:7], v[162:165], v[210:213], v[4:7]
	v_mfma_f32_16x16x32_bf16 v[0:3], v[178:181], v[210:213], v[0:3]
	s_setprio 0
	s_barrier
	v_add_u32_e32 v140, s64, v141
	ds_read_b128 v[134:137], v140
	ds_read_b128 v[146:149], v140 offset:1024
	ds_read_b128 v[150:153], v140 offset:2048
	ds_read_b128 v[154:157], v140 offset:3072
	v_add_u32_e32 v140, s63, v141
	ds_read_b128 v[158:161], v140
	ds_read_b128 v[162:165], v140 offset:1024
	ds_read_b128 v[174:177], v140 offset:2048
	ds_read_b128 v[178:181], v140 offset:3072
	s_mov_b32 m0, s53
	v_lshl_add_u64 v[216:217], s[40:41], 0, v[128:129]
	ds_read_b128 v[182:185], v145 offset:32768
	ds_read_b128 v[186:189], v145 offset:33792
	ds_read_b128 v[190:193], v145 offset:34816
	ds_read_b128 v[194:197], v145 offset:35840
	ds_read_b128 v[198:201], v145 offset:36864
	ds_read_b128 v[202:205], v145 offset:37888
	ds_read_b128 v[206:209], v145 offset:38912
	ds_read_b128 v[210:213], v145 offset:39936
	global_load_lds_dwordx4 v[216:217], off
	v_lshl_add_u64 v[216:217], s[40:41], 0, v[130:131]
	s_mov_b32 m0, s54
	s_nop 0
	global_load_lds_dwordx4 v[216:217], off
	s_waitcnt vmcnt(8)
	s_waitcnt lgkmcnt(0)
	s_barrier
	s_setprio 1
	s_waitcnt lgkmcnt(0)
	v_mfma_f32_16x16x32_bf16 v[124:127], v[134:137], v[182:185], v[124:127]
	v_mfma_f32_16x16x32_bf16 v[120:123], v[150:153], v[182:185], v[120:123]
	v_mfma_f32_16x16x32_bf16 v[108:111], v[134:137], v[190:193], v[108:111]
	v_mfma_f32_16x16x32_bf16 v[104:107], v[150:153], v[190:193], v[104:107]
	v_mfma_f32_16x16x32_bf16 v[92:95], v[134:137], v[198:201], v[92:95]
	v_mfma_f32_16x16x32_bf16 v[88:91], v[150:153], v[198:201], v[88:91]
	v_mfma_f32_16x16x32_bf16 v[76:79], v[134:137], v[206:209], v[76:79]
	v_mfma_f32_16x16x32_bf16 v[72:75], v[150:153], v[206:209], v[72:75]
	v_mfma_f32_16x16x32_bf16 v[124:127], v[146:149], v[186:189], v[124:127]
	v_mfma_f32_16x16x32_bf16 v[120:123], v[154:157], v[186:189], v[120:123]
	v_mfma_f32_16x16x32_bf16 v[108:111], v[146:149], v[194:197], v[108:111]
	v_mfma_f32_16x16x32_bf16 v[104:107], v[154:157], v[194:197], v[104:107]
	v_mfma_f32_16x16x32_bf16 v[92:95], v[146:149], v[202:205], v[92:95]
	v_mfma_f32_16x16x32_bf16 v[88:91], v[154:157], v[202:205], v[88:91]
	v_mfma_f32_16x16x32_bf16 v[76:79], v[146:149], v[210:213], v[76:79]
	v_mfma_f32_16x16x32_bf16 v[72:75], v[154:157], v[210:213], v[72:75]
	v_mfma_f32_16x16x32_bf16 v[116:119], v[158:161], v[182:185], v[116:119]
	v_mfma_f32_16x16x32_bf16 v[112:115], v[174:177], v[182:185], v[112:115]
	v_mfma_f32_16x16x32_bf16 v[100:103], v[158:161], v[190:193], v[100:103]
	v_mfma_f32_16x16x32_bf16 v[96:99], v[174:177], v[190:193], v[96:99]
	v_mfma_f32_16x16x32_bf16 v[84:87], v[158:161], v[198:201], v[84:87]
	v_mfma_f32_16x16x32_bf16 v[80:83], v[174:177], v[198:201], v[80:83]
	v_mfma_f32_16x16x32_bf16 v[68:71], v[158:161], v[206:209], v[68:71]
	v_mfma_f32_16x16x32_bf16 v[64:67], v[174:177], v[206:209], v[64:67]
	v_mfma_f32_16x16x32_bf16 v[116:119], v[162:165], v[186:189], v[116:119]
	v_mfma_f32_16x16x32_bf16 v[112:115], v[178:181], v[186:189], v[112:115]
	v_mfma_f32_16x16x32_bf16 v[100:103], v[162:165], v[194:197], v[100:103]
	v_mfma_f32_16x16x32_bf16 v[96:99], v[178:181], v[194:197], v[96:99]
	v_mfma_f32_16x16x32_bf16 v[84:87], v[162:165], v[202:205], v[84:87]
	v_mfma_f32_16x16x32_bf16 v[80:83], v[178:181], v[202:205], v[80:83]
	v_mfma_f32_16x16x32_bf16 v[68:71], v[162:165], v[210:213], v[68:71]
	v_mfma_f32_16x16x32_bf16 v[64:67], v[178:181], v[210:213], v[64:67]
	s_setprio 0
	s_barrier
; #define PG8_STAGE(bufoff, gbase, voff) do { _Pragma("unroll") for (int _i = 0; _i < 2; ++_i) \
;         __builtin_amdgcn_global_load_lds((const unsigned*)((const char*)(gbase) + (voff)[_i]), (LAS unsigned*)(lds + (bufoff) + ldsw + _i * 8192), 16, 0, 0); } while (0)
; #define PG8_LDA(dst, b, h) do { _Pragma("unroll") for (int m = 0; m < 4; ++m) _Pragma("unroll") for (int k = 0; k < 2; ++k) dst[m][k] = *(const LAS bf16x8*)(lds + PG8_SA(b, h) + aoff + m * 2048 + k * 1024); } while (0)
; #define PG8_MMA(ai, bj, At, Bt) do { __builtin_amdgcn_s_setprio(1); _Pragma("unroll") for (int k = 0; k < 2; ++k) _Pragma("unroll") for (int m = 0; m < 4; ++m) _Pragma("unroll") for (int n = 0; n < 2; ++n) \
;         acc[ai][bj][m][n] = __builtin_amdgcn_mfma_f32_16x16x32_bf16(Bt[n][k], At[m][k], acc[ai][bj][m][n], 0, 0, 0); __builtin_amdgcn_s_setprio(0); } while (0)
; #define PG8_WAIT_V(n) asm volatile("s_waitcnt vmcnt(" #n ")" ::: "memory")
; #define PG8_WAIT_L(n) asm volatile("s_waitcnt lgkmcnt(" #n ")" ::: "memory")
; #define PG8_BAR __builtin_amdgcn_s_barrier()
; #define PG8_SCHED __builtin_amdgcn_sched_barrier(0)
; template <class Epi, bool ALIGN_EPI>
; __device__ __forceinline__ void gemm_phase(LAS unsigned char* lds, const Gemm g, const StaticOrder& S, const Epi& E, const int tid) {
;     ...
;             PG8_LDA(At, 1, 1); PG8_STAGE(PG8_SB(1, 0), b3, voffB); PG8_STAGE(PG8_SB(1, 1), b3 + hB, voffB); PG8_STAGE(PG8_SA(1, 0), a3, voffA);
;             PG8_WAIT_V(8); PG8_WAIT_L(0); PG8_BAR; PG8_MMA(1, 0, At, B0); PG8_MMA(1, 1, At, B1); PG8_BAR; PG8_SCHED;
;         }
;         if constexpr (ALIGN_EPI) { if (wr == 0) PG8_BAR; }
	s_mov_b32 m0, s62
	v_lshl_add_u64 v[138:139], v[138:139], 0, s[92:93]
	ds_read_b128 v[182:185], v145 offset:49152
	ds_read_b128 v[186:189], v145 offset:50176
	ds_read_b128 v[190:193], v145 offset:51200
	ds_read_b128 v[194:197], v145 offset:52224
	ds_read_b128 v[198:201], v145 offset:53248
	ds_read_b128 v[202:205], v145 offset:54272
	ds_read_b128 v[206:209], v145 offset:55296
	ds_read_b128 v[210:213], v145 offset:56320
	global_load_lds_dwordx4 v[138:139], off
	v_lshl_add_u64 v[138:139], v[142:143], 0, s[92:93]
	s_mov_b32 m0, s61
	s_nop 0
	global_load_lds_dwordx4 v[138:139], off
	v_lshl_add_u64 v[138:139], s[38:39], 0, v[168:169]
	s_mov_b32 m0, s70
	s_nop 0
	global_load_lds_dwordx4 v[138:139], off
	v_lshl_add_u64 v[138:139], s[38:39], 0, v[132:133]
	s_mov_b32 m0, s69
	s_nop 0
	global_load_lds_dwordx4 v[138:139], off
	v_lshl_add_u64 v[138:139], v[166:167], 0, s[92:93]
	s_mov_b32 m0, s55
	s_nop 0
	global_load_lds_dwordx4 v[138:139], off
	v_lshl_add_u64 v[138:139], v[214:215], 0, s[92:93]
	s_mov_b32 m0, s56
	s_nop 0
	global_load_lds_dwordx4 v[138:139], off
	s_waitcnt vmcnt(8)
	s_waitcnt lgkmcnt(0)
	s_barrier
	s_setprio 1
	s_waitcnt lgkmcnt(0)
	v_mfma_f32_16x16x32_bf16 v[60:63], v[134:137], v[182:185], v[60:63]
	v_mfma_f32_16x16x32_bf16 v[56:59], v[150:153], v[182:185], v[56:59]
	v_mfma_f32_16x16x32_bf16 v[48:51], v[134:137], v[190:193], v[48:51]
	v_mfma_f32_16x16x32_bf16 v[40:43], v[150:153], v[190:193], v[40:43]
	v_mfma_f32_16x16x32_bf16 v[32:35], v[134:137], v[198:201], v[32:35]
	v_mfma_f32_16x16x32_bf16 v[24:27], v[150:153], v[198:201], v[24:27]
	v_mfma_f32_16x16x32_bf16 v[16:19], v[134:137], v[206:209], v[16:19]
	v_mfma_f32_16x16x32_bf16 v[8:11], v[150:153], v[206:209], v[8:11]
	v_mfma_f32_16x16x32_bf16 v[60:63], v[146:149], v[186:189], v[60:63]
	v_mfma_f32_16x16x32_bf16 v[56:59], v[154:157], v[186:189], v[56:59]
	v_mfma_f32_16x16x32_bf16 v[48:51], v[146:149], v[194:197], v[48:51]
	v_mfma_f32_16x16x32_bf16 v[40:43], v[154:157], v[194:197], v[40:43]
	v_mfma_f32_16x16x32_bf16 v[32:35], v[146:149], v[202:205], v[32:35]
	v_mfma_f32_16x16x32_bf16 v[24:27], v[154:157], v[202:205], v[24:27]
	v_mfma_f32_16x16x32_bf16 v[16:19], v[146:149], v[210:213], v[16:19]
	v_mfma_f32_16x16x32_bf16 v[8:11], v[154:157], v[210:213], v[8:11]
	v_mfma_f32_16x16x32_bf16 v[52:55], v[158:161], v[182:185], v[52:55]
	v_mfma_f32_16x16x32_bf16 v[44:47], v[174:177], v[182:185], v[44:47]
	v_mfma_f32_16x16x32_bf16 v[36:39], v[158:161], v[190:193], v[36:39]
	v_mfma_f32_16x16x32_bf16 v[28:31], v[174:177], v[190:193], v[28:31]
	v_mfma_f32_16x16x32_bf16 v[20:23], v[158:161], v[198:201], v[20:23]
	v_mfma_f32_16x16x32_bf16 v[12:15], v[174:177], v[198:201], v[12:15]
	v_mfma_f32_16x16x32_bf16 v[4:7], v[158:161], v[206:209], v[4:7]
	v_mfma_f32_16x16x32_bf16 v[0:3], v[174:177], v[206:209], v[0:3]
	v_mfma_f32_16x16x32_bf16 v[52:55], v[162:165], v[186:189], v[52:55]
	v_mfma_f32_16x16x32_bf16 v[44:47], v[178:181], v[186:189], v[44:47]
	v_mfma_f32_16x16x32_bf16 v[36:39], v[162:165], v[194:197], v[36:39]
	v_mfma_f32_16x16x32_bf16 v[28:31], v[178:181], v[194:197], v[28:31]
	v_mfma_f32_16x16x32_bf16 v[20:23], v[162:165], v[202:205], v[20:23]
	v_mfma_f32_16x16x32_bf16 v[12:15], v[178:181], v[202:205], v[12:15]
	v_mfma_f32_16x16x32_bf16 v[4:7], v[162:165], v[210:213], v[4:7]
	v_mfma_f32_16x16x32_bf16 v[0:3], v[178:181], v[210:213], v[0:3]
	s_setprio 0
	s_barrier
	s_movk_i32 s40, 0x100
	s_andn2_b64 vcc, exec, s[36:37]
	s_mov_b64 s[38:39], -1
	s_mov_b64 s[36:37], 0
	s_cbranch_vccz .LBB0_379
	v_readlane_b32 s60, v255, 51
	s_and_b64 vcc, exec, s[12:13]
	v_readlane_b32 s61, v255, 52
	s_cbranch_vccz .LBB0_382
	s_barrier
